# code placement: combo15 with the five K-loop head labels aligned to 64 bytes (instruction cache line)
# speedup vs baseline: 1.0081x; 1.0081x over previous
;     __device__ __forceinline__ bool next(int i, Unit& u) const { const int off = i * H + (r >> 1); if (off >= 8 * nN) return false; u.pm = 16 * g + 8 * (r & 1) + (off & 7); u.pn = off >> 3; return true; }
; #define PG8_STAGE(bufoff, gbase, unused) do { _Pragma("unroll") for (int _i = 0; _i < 2; ++_i) \
;         __builtin_amdgcn_global_load_lds((const unsigned*)((const char*)(gbase) + voff + _i * 8192), (LAS unsigned*)(lds + (bufoff) + ldsw + _i * 8192), 16, 0, 0); } while (0)
; #define PG8_LDA(dst, b, h) do { _Pragma("unroll") for (int m = 0; m < 4; ++m) _Pragma("unroll") for (int k = 0; k < 2; ++k) dst[m][k] = *(const LAS bf16x8*)(lds + PG8_SA(b, h) + aoff + m * 2048 + (FP8 ? k * 16 : k * 1024)); } while (0)
; #define PG8_LDB(dst, b, h) do { _Pragma("unroll") for (int n = 0; n < 2; ++n) _Pragma("unroll") for (int k = 0; k < 2; ++k) dst[n][k] = *(const LAS bf16x8*)(lds + PG8_SB(b, h) + boff + n * 2048 + (FP8 ? k * 16 : k * 1024)); } while (0)
; #define PG8_BAR __builtin_amdgcn_s_barrier()
; template <class Epi, class Sched, bool ALIGN_EPI, bool SP2, int MODE  >
; __device__ __forceinline__ void gemm_phase(LAS unsigned char* lds, const Gemm g, const Sched S, const Epi E, unsigned long long& probe_acc, int epi_id, int wv) {
;     ...
;         const bool has_next = S.next(ui + 1, nxt);
;         const char* nA = has_next ? (const char*)g.A + (size_t)nxt.pm * tA + (g.gt ? (size_t)(nxt.pn / g.gt) * gK2 : 0) : cA; const char* nB = has_next ? (const char*)g.Bt + (size_t)nxt.pn * tB : cB;
;         for (int t = 0; t < nt; t += 2) {
;             const bool last = (t == nt - 2);
;             const char* a1 = cA + (size_t)(t + 1) * kstep;
;             const char* a2 = last ? nA : cA + (size_t)(t + 2) * kstep; const char* b2 = last ? nB : cB + (size_t)(t + 2) * kstep;
;             const char* a3 = a2 + kstep; const char* b3 = b2 + kstep;
;             if constexpr (SP2) {
;             PG8_LDB(B0, 0, 0); PG8_LDB(B1, 0, 1); PG8_SCHED; PG8_LDA(At, 0, 0); PG8_STAGE(PG8_SA(1, 1), a1 + hA, voffA);
;             PG8_WAIT_V(8); PG8_WAIT_L(0); PG8_BAR; PG8_MMA(0, 0, At, B0); PG8_MMA(0, 1, At, B1); PG8_BAR; PG8_SCHED;
;             PG8_LDA(At, 0, 1); PG8_STAGE(PG8_SB(0, 0), b2, voffB); PG8_STAGE(PG8_SB(0, 1), b2 + hB, voffB); PG8_STAGE(PG8_SA(0, 0), a2, voffA);
;             PG8_WAIT_V(8); PG8_WAIT_L(0); PG8_BAR; PG8_MMA(1, 0, At, B0); PG8_MMA(1, 1, At, B1); PG8_BAR; PG8_SCHED;
.LBB0_325:
	s_mov_b64 s[28:29], s[10:11]
	s_mov_b32 s11, s1
	s_mov_b32 s26, s1
	s_add_i32 s40, s40, 1
	v_readlane_b32 s1, v254, 6
	s_mov_b64 s[14:15], s[4:5]
	s_mul_i32 s1, s40, s1
	v_readlane_b32 s4, v254, 35
	s_add_i32 s1, s1, s4
	s_cmpk_lt_i32 s1, 0x160
	s_cselect_b64 s[24:25], -1, 0
	s_and_b32 s4, s1, 7
	v_readlane_b32 s5, v254, 18
	s_mov_b32 s10, s69
	s_mov_b32 s8, s69
	s_or_b32 s69, s4, s5
	s_ashr_i32 s1, s1, 3
	s_and_b64 s[4:5], s[24:25], exec
	s_cselect_b32 s10, s69, s10
	s_cselect_b32 s4, s1, s11
	s_ashr_i32 s11, s10, 31
	s_lshl_b64 s[10:11], s[10:11], 19
	s_add_u32 s10, s34, s10
	s_addc_u32 s11, s35, s11
	s_and_b64 s[16:17], s[24:25], exec
	s_cselect_b32 s27, s11, s29
	s_cselect_b32 s46, s10, s28
	s_ashr_i32 s5, s4, 31
	s_lshl_b64 s[4:5], s[4:5], 19
	s_add_u32 s4, s36, s4
	s_addc_u32 s5, s37, s5
	s_and_b64 s[16:17], s[24:25], exec
	s_cselect_b32 vcc_lo, s5, s15
	s_cselect_b32 vcc_hi, s4, s14
	s_add_u32 s16, s14, 0x8000
	s_addc_u32 s17, s15, 0
	s_mov_b32 s14, -2
	s_waitcnt lgkmcnt(0)
	v_add_u32_e32 v0, s39, v212
	ds_read_b128 v[132:135], v0
	ds_read_b128 v[136:139], v0 offset:1024
	ds_read_b128 v[140:143], v0 offset:2048
	ds_read_b128 v[144:147], v0 offset:3072
	v_add_u32_e32 v0, s65, v212
	ds_read_b128 v[148:151], v0
	ds_read_b128 v[152:155], v0 offset:1024
	ds_read_b128 v[156:159], v0 offset:2048
	ds_read_b128 v[160:163], v0 offset:3072
	s_add_u32 s30, s28, 0x8000
	s_addc_u32 s31, s29, 0
	s_cmp_eq_u32 s14, 12
	s_cselect_b32 s23, s27, s31
	s_cselect_b32 s22, s46, s30
	s_cselect_b32 s21, vcc_lo, s17
	s_cselect_b32 s20, vcc_hi, s16
	v_lshl_add_u64 v[184:185], s[28:29], 0, v[130:131]
	v_lshl_add_u64 v[204:205], v[184:185], 0, s[80:81]
	s_add_i32 m0, s85, 0xc000
	ds_read_b128 v[164:167], v213
	ds_read_b128 v[168:171], v213 offset:1024
	ds_read_b128 v[172:175], v213 offset:2048
	ds_read_b128 v[176:179], v213 offset:3072
	ds_read_b128 v[180:183], v213 offset:4096
	ds_read_b128 v[190:193], v213 offset:5120
	ds_read_b128 v[196:199], v213 offset:6144
	ds_read_b128 v[200:203], v213 offset:7168
	global_load_lds_dwordx4 v[204:205], off
	v_lshl_add_u64 v[184:185], v[184:185], 0, s[82:83]
	s_add_i32 m0, s85, 0xe000
	s_nop 0
	global_load_lds_dwordx4 v[184:185], off
	s_waitcnt vmcnt(8)
	s_waitcnt lgkmcnt(0)
	s_setprio 1
	s_barrier
	v_mfma_i32_16x16x64_i8 v[126:129], v[132:135], v[164:167], 0
	v_mfma_i32_16x16x64_i8 v[102:105], v[140:143], v[164:167], 0
	v_mfma_i32_16x16x64_i8 v[122:125], v[132:135], v[172:175], 0
	v_mfma_i32_16x16x64_i8 v[94:97], v[140:143], v[172:175], 0
	v_mfma_i32_16x16x64_i8 v[118:121], v[132:135], v[180:183], 0
	v_mfma_i32_16x16x64_i8 v[46:49], v[140:143], v[180:183], 0
	v_mfma_i32_16x16x64_i8 v[110:113], v[132:135], v[196:199], 0
	v_mfma_i32_16x16x64_i8 v[38:41], v[140:143], v[196:199], 0
	v_mfma_i32_16x16x64_i8 v[126:129], v[136:139], v[168:171], v[126:129]
	v_mfma_i32_16x16x64_i8 v[102:105], v[144:147], v[168:171], v[102:105]
	v_mfma_i32_16x16x64_i8 v[122:125], v[136:139], v[176:179], v[122:125]
	v_mfma_i32_16x16x64_i8 v[94:97], v[144:147], v[176:179], v[94:97]
	v_mfma_i32_16x16x64_i8 v[118:121], v[136:139], v[190:193], v[118:121]
	v_mfma_i32_16x16x64_i8 v[46:49], v[144:147], v[190:193], v[46:49]
	v_mfma_i32_16x16x64_i8 v[110:113], v[136:139], v[200:203], v[110:113]
	v_mfma_i32_16x16x64_i8 v[38:41], v[144:147], v[200:203], v[38:41]
	v_mfma_i32_16x16x64_i8 v[114:117], v[148:151], v[164:167], 0
	v_mfma_i32_16x16x64_i8 v[82:85], v[156:159], v[164:167], 0
	v_mfma_i32_16x16x64_i8 v[106:109], v[148:151], v[172:175], 0
	v_mfma_i32_16x16x64_i8 v[74:77], v[156:159], v[172:175], 0
	v_mfma_i32_16x16x64_i8 v[98:101], v[148:151], v[180:183], 0
	v_mfma_i32_16x16x64_i8 v[42:45], v[156:159], v[180:183], 0
	v_mfma_i32_16x16x64_i8 v[90:93], v[148:151], v[196:199], 0
	v_mfma_i32_16x16x64_i8 v[34:37], v[156:159], v[196:199], 0
	v_mfma_i32_16x16x64_i8 v[114:117], v[152:155], v[168:171], v[114:117]
	v_mfma_i32_16x16x64_i8 v[82:85], v[160:163], v[168:171], v[82:85]
	v_mfma_i32_16x16x64_i8 v[106:109], v[152:155], v[176:179], v[106:109]
	v_mfma_i32_16x16x64_i8 v[74:77], v[160:163], v[176:179], v[74:77]
	v_mfma_i32_16x16x64_i8 v[98:101], v[152:155], v[190:193], v[98:101]
	v_mfma_i32_16x16x64_i8 v[42:45], v[160:163], v[190:193], v[42:45]
	v_mfma_i32_16x16x64_i8 v[90:93], v[152:155], v[200:203], v[90:93]
	v_mfma_i32_16x16x64_i8 v[34:37], v[160:163], v[200:203], v[34:37]
	s_barrier
	s_setprio 0
	s_mov_b32 m0, s41
	v_lshl_add_u64 v[184:185], s[20:21], 0, v[130:131]
	ds_read_b128 v[164:167], v213 offset:16384
	ds_read_b128 v[168:171], v213 offset:17408
	ds_read_b128 v[172:175], v213 offset:18432
	ds_read_b128 v[176:179], v213 offset:19456
	ds_read_b128 v[180:183], v213 offset:20480
	ds_read_b128 v[190:193], v213 offset:21504
	ds_read_b128 v[196:199], v213 offset:22528
	ds_read_b128 v[200:203], v213 offset:23552
	global_load_lds_dwordx4 v[184:185], off
	v_lshl_add_u64 v[204:205], v[184:185], 0, s[70:71]
	s_mov_b32 m0, s64
	s_nop 0
	global_load_lds_dwordx4 v[204:205], off
	v_lshl_add_u64 v[204:205], v[184:185], 0, s[72:73]
	s_mov_b32 m0, s68
	s_nop 0
	global_load_lds_dwordx4 v[204:205], off
	v_lshl_add_u64 v[204:205], v[184:185], 0, s[74:75]
	s_mov_b32 m0, s84
	s_nop 0
	global_load_lds_dwordx4 v[204:205], off
	v_lshl_add_u64 v[204:205], s[22:23], 0, v[130:131]
	s_mov_b32 m0, s85
	v_lshl_add_u64 v[206:207], v[204:205], 0, s[70:71]
	global_load_lds_dwordx4 v[204:205], off
	s_mov_b32 m0, s86
	s_nop 0
	global_load_lds_dwordx4 v[206:207], off
	s_waitcnt vmcnt(8)
	s_waitcnt lgkmcnt(0)
	s_setprio 1
	s_barrier
; #define PG8_STAGE(bufoff, gbase, unused) do { _Pragma("unroll") for (int _i = 0; _i < 2; ++_i) \
;         __builtin_amdgcn_global_load_lds((const unsigned*)((const char*)(gbase) + voff + _i * 8192), (LAS unsigned*)(lds + (bufoff) + ldsw + _i * 8192), 16, 0, 0); } while (0)
; #define PG8_LDA(dst, b, h) do { _Pragma("unroll") for (int m = 0; m < 4; ++m) _Pragma("unroll") for (int k = 0; k < 2; ++k) dst[m][k] = *(const LAS bf16x8*)(lds + PG8_SA(b, h) + aoff + m * 2048 + (FP8 ? k * 16 : k * 1024)); } while (0)
; #define PG8_LDB(dst, b, h) do { _Pragma("unroll") for (int n = 0; n < 2; ++n) _Pragma("unroll") for (int k = 0; k < 2; ++k) dst[n][k] = *(const LAS bf16x8*)(lds + PG8_SB(b, h) + boff + n * 2048 + (FP8 ? k * 16 : k * 1024)); } while (0)
; #define PG8_WAIT_V(n) asm volatile("s_waitcnt vmcnt(" #n ")" ::: "memory")
; #define PG8_WAIT_L(n) asm volatile("s_waitcnt lgkmcnt(" #n ")" ::: "memory")
; #define PG8_BAR __builtin_amdgcn_s_barrier()
; #define PG8_SCHED __builtin_amdgcn_sched_barrier(0)
; template <class Epi, class Sched, bool ALIGN_EPI, bool SP2, int MODE  >
; __device__ __forceinline__ void gemm_phase(LAS unsigned char* lds, const Gemm g, const Sched S, const Epi E, unsigned long long& probe_acc, int epi_id, int wv) {
;     ...
;             PG8_WAIT_V(8); PG8_WAIT_L(0); PG8_BAR; PG8_MMA(1, 0, At, B0); PG8_MMA(1, 1, At, B1); PG8_BAR; PG8_SCHED;
;             PG8_LDB(B0, 1, 0); PG8_LDB(B1, 1, 1); PG8_SCHED; PG8_LDA(At, 1, 0); PG8_STAGE(PG8_SA(0, 1), a2 + hA, voffA);
;             PG8_WAIT_V(8); PG8_WAIT_L(0); PG8_BAR; PG8_MMA(0, 0, At, B0); PG8_MMA(0, 1, At, B1); PG8_BAR; PG8_SCHED;
	v_mfma_i32_16x16x64_i8 v[86:89], v[132:135], v[164:167], 0
	v_mfma_i32_16x16x64_i8 v[30:33], v[140:143], v[164:167], 0
	v_mfma_i32_16x16x64_i8 v[78:81], v[132:135], v[172:175], 0
	v_mfma_i32_16x16x64_i8 v[22:25], v[140:143], v[172:175], 0
	v_mfma_i32_16x16x64_i8 v[70:73], v[132:135], v[180:183], 0
	v_mfma_i32_16x16x64_i8 v[14:17], v[140:143], v[180:183], 0
	v_mfma_i32_16x16x64_i8 v[62:65], v[132:135], v[196:199], 0
	v_mfma_i32_16x16x64_i8 v[2:5], v[140:143], v[196:199], 0
	v_mfma_i32_16x16x64_i8 v[86:89], v[136:139], v[168:171], v[86:89]
	v_mfma_i32_16x16x64_i8 v[30:33], v[144:147], v[168:171], v[30:33]
	v_mfma_i32_16x16x64_i8 v[78:81], v[136:139], v[176:179], v[78:81]
	v_mfma_i32_16x16x64_i8 v[22:25], v[144:147], v[176:179], v[22:25]
	v_mfma_i32_16x16x64_i8 v[70:73], v[136:139], v[190:193], v[70:73]
	v_mfma_i32_16x16x64_i8 v[14:17], v[144:147], v[190:193], v[14:17]
	v_mfma_i32_16x16x64_i8 v[62:65], v[136:139], v[200:203], v[62:65]
	v_mfma_i32_16x16x64_i8 v[2:5], v[144:147], v[200:203], v[2:5]
	v_mfma_i32_16x16x64_i8 v[66:69], v[148:151], v[164:167], 0
	v_mfma_i32_16x16x64_i8 v[26:29], v[156:159], v[164:167], 0
	v_mfma_i32_16x16x64_i8 v[58:61], v[148:151], v[172:175], 0
	v_mfma_i32_16x16x64_i8 v[18:21], v[156:159], v[172:175], 0
	v_mfma_i32_16x16x64_i8 v[54:57], v[148:151], v[180:183], 0
	v_mfma_i32_16x16x64_i8 v[10:13], v[156:159], v[180:183], 0
	v_mfma_i32_16x16x64_i8 v[50:53], v[148:151], v[196:199], 0
	v_mfma_i32_16x16x64_i8 v[6:9], v[156:159], v[196:199], 0
	v_mfma_i32_16x16x64_i8 v[66:69], v[152:155], v[168:171], v[66:69]
	v_mfma_i32_16x16x64_i8 v[26:29], v[160:163], v[168:171], v[26:29]
	v_mfma_i32_16x16x64_i8 v[58:61], v[152:155], v[176:179], v[58:61]
	v_mfma_i32_16x16x64_i8 v[18:21], v[160:163], v[176:179], v[18:21]
	v_mfma_i32_16x16x64_i8 v[54:57], v[152:155], v[190:193], v[54:57]
	v_mfma_i32_16x16x64_i8 v[10:13], v[160:163], v[190:193], v[10:13]
	v_mfma_i32_16x16x64_i8 v[50:53], v[152:155], v[200:203], v[50:53]
	v_mfma_i32_16x16x64_i8 v[6:9], v[160:163], v[200:203], v[6:9]
	s_barrier
	s_setprio 0
	v_add_u32_e32 v0, s90, v212
	ds_read_b128 v[132:135], v0
	ds_read_b128 v[136:139], v0 offset:1024
	ds_read_b128 v[140:143], v0 offset:2048
	ds_read_b128 v[144:147], v0 offset:3072
	v_add_u32_e32 v0, s95, v212
	ds_read_b128 v[148:151], v0
	ds_read_b128 v[152:155], v0 offset:1024
	ds_read_b128 v[156:159], v0 offset:2048
	ds_read_b128 v[160:163], v0 offset:3072
	s_mov_b32 m0, s87
	v_lshl_add_u64 v[206:207], v[204:205], 0, s[72:73]
	ds_read_b128 v[164:167], v213 offset:32768
	ds_read_b128 v[168:171], v213 offset:33792
	ds_read_b128 v[172:175], v213 offset:34816
	ds_read_b128 v[176:179], v213 offset:35840
	ds_read_b128 v[180:183], v213 offset:36864
	ds_read_b128 v[190:193], v213 offset:37888
	ds_read_b128 v[196:199], v213 offset:38912
	ds_read_b128 v[200:203], v213 offset:39936
	global_load_lds_dwordx4 v[206:207], off
	v_lshl_add_u64 v[206:207], v[204:205], 0, s[74:75]
	s_mov_b32 m0, s88
	s_nop 0
	global_load_lds_dwordx4 v[206:207], off
	s_waitcnt vmcnt(8)
	s_waitcnt lgkmcnt(0)
	s_setprio 1
	s_barrier
	v_mfma_i32_16x16x64_i8 v[126:129], v[132:135], v[164:167], v[126:129]
	v_mfma_i32_16x16x64_i8 v[102:105], v[140:143], v[164:167], v[102:105]
	v_mfma_i32_16x16x64_i8 v[122:125], v[132:135], v[172:175], v[122:125]
	v_mfma_i32_16x16x64_i8 v[94:97], v[140:143], v[172:175], v[94:97]
	v_mfma_i32_16x16x64_i8 v[118:121], v[132:135], v[180:183], v[118:121]
	v_mfma_i32_16x16x64_i8 v[46:49], v[140:143], v[180:183], v[46:49]
	v_mfma_i32_16x16x64_i8 v[110:113], v[132:135], v[196:199], v[110:113]
	v_mfma_i32_16x16x64_i8 v[38:41], v[140:143], v[196:199], v[38:41]
	v_mfma_i32_16x16x64_i8 v[126:129], v[136:139], v[168:171], v[126:129]
	v_mfma_i32_16x16x64_i8 v[102:105], v[144:147], v[168:171], v[102:105]
	v_mfma_i32_16x16x64_i8 v[122:125], v[136:139], v[176:179], v[122:125]
	v_mfma_i32_16x16x64_i8 v[94:97], v[144:147], v[176:179], v[94:97]
	v_mfma_i32_16x16x64_i8 v[118:121], v[136:139], v[190:193], v[118:121]
	v_mfma_i32_16x16x64_i8 v[46:49], v[144:147], v[190:193], v[46:49]
	v_mfma_i32_16x16x64_i8 v[110:113], v[136:139], v[200:203], v[110:113]
	v_mfma_i32_16x16x64_i8 v[38:41], v[144:147], v[200:203], v[38:41]
	v_mfma_i32_16x16x64_i8 v[114:117], v[148:151], v[164:167], v[114:117]
	v_mfma_i32_16x16x64_i8 v[82:85], v[156:159], v[164:167], v[82:85]
	v_mfma_i32_16x16x64_i8 v[106:109], v[148:151], v[172:175], v[106:109]
	v_mfma_i32_16x16x64_i8 v[74:77], v[156:159], v[172:175], v[74:77]
	v_mfma_i32_16x16x64_i8 v[98:101], v[148:151], v[180:183], v[98:101]
	v_mfma_i32_16x16x64_i8 v[42:45], v[156:159], v[180:183], v[42:45]
	v_mfma_i32_16x16x64_i8 v[90:93], v[148:151], v[196:199], v[90:93]
	v_mfma_i32_16x16x64_i8 v[34:37], v[156:159], v[196:199], v[34:37]
	v_mfma_i32_16x16x64_i8 v[114:117], v[152:155], v[168:171], v[114:117]
	v_mfma_i32_16x16x64_i8 v[82:85], v[160:163], v[168:171], v[82:85]
	v_mfma_i32_16x16x64_i8 v[106:109], v[152:155], v[176:179], v[106:109]
	v_mfma_i32_16x16x64_i8 v[74:77], v[160:163], v[176:179], v[74:77]
	v_mfma_i32_16x16x64_i8 v[98:101], v[152:155], v[190:193], v[98:101]
	v_mfma_i32_16x16x64_i8 v[42:45], v[160:163], v[190:193], v[42:45]
	v_mfma_i32_16x16x64_i8 v[90:93], v[152:155], v[200:203], v[90:93]
	v_mfma_i32_16x16x64_i8 v[34:37], v[160:163], v[200:203], v[34:37]
	s_barrier
; #define PG8_STAGE(bufoff, gbase, unused) do { _Pragma("unroll") for (int _i = 0; _i < 2; ++_i) \
;         __builtin_amdgcn_global_load_lds((const unsigned*)((const char*)(gbase) + voff + _i * 8192), (LAS unsigned*)(lds + (bufoff) + ldsw + _i * 8192), 16, 0, 0); } while (0)
; #define PG8_LDA(dst, b, h) do { _Pragma("unroll") for (int m = 0; m < 4; ++m) _Pragma("unroll") for (int k = 0; k < 2; ++k) dst[m][k] = *(const LAS bf16x8*)(lds + PG8_SA(b, h) + aoff + m * 2048 + (FP8 ? k * 16 : k * 1024)); } while (0)
; #define PG8_WAIT_V(n) asm volatile("s_waitcnt vmcnt(" #n ")" ::: "memory")
; #define PG8_WAIT_L(n) asm volatile("s_waitcnt lgkmcnt(" #n ")" ::: "memory")
; #define PG8_BAR __builtin_amdgcn_s_barrier()
; #define PG8_SCHED __builtin_amdgcn_sched_barrier(0)
; template <class Epi, class Sched, bool ALIGN_EPI, bool SP2, int MODE  >
; __device__ __forceinline__ void gemm_phase(LAS unsigned char* lds, const Gemm g, const Sched S, const Epi E, unsigned long long& probe_acc, int epi_id, int wv) {
;     ...
;             PG8_WAIT_V(8); PG8_WAIT_L(0); PG8_BAR; PG8_MMA(0, 0, At, B0); PG8_MMA(0, 1, At, B1); PG8_BAR; PG8_SCHED;
;             PG8_LDA(At, 1, 1); PG8_STAGE(PG8_SB(1, 0), b3, voffB); PG8_STAGE(PG8_SB(1, 1), b3 + hB, voffB); PG8_STAGE(PG8_SA(1, 0), a3, voffA);
;             PG8_WAIT_V(8); PG8_WAIT_L(0); PG8_BAR; PG8_MMA(1, 0, At, B0); PG8_MMA(1, 1, At, B1); PG8_BAR; PG8_SCHED;
	s_setprio 0
	s_mov_b32 m0, s91
	v_lshl_add_u64 v[206:207], v[184:185], 0, s[76:77]
	ds_read_b128 v[164:167], v213 offset:49152
	ds_read_b128 v[168:171], v213 offset:50176
	ds_read_b128 v[172:175], v213 offset:51200
	ds_read_b128 v[176:179], v213 offset:52224
	ds_read_b128 v[180:183], v213 offset:53248
	ds_read_b128 v[190:193], v213 offset:54272
	ds_read_b128 v[196:199], v213 offset:55296
	ds_read_b128 v[200:203], v213 offset:56320
	global_load_lds_dwordx4 v[206:207], off
	v_lshl_add_u64 v[206:207], v[184:185], 0, s[78:79]
	s_mov_b32 m0, s92
	s_nop 0
	global_load_lds_dwordx4 v[206:207], off
	v_lshl_add_u64 v[206:207], v[184:185], 0, s[80:81]
	s_mov_b32 m0, s2
	v_lshl_add_u64 v[184:185], v[184:185], 0, s[82:83]
	global_load_lds_dwordx4 v[206:207], off
	s_mov_b32 m0, s3
	s_nop 0
	global_load_lds_dwordx4 v[184:185], off
	v_lshl_add_u64 v[184:185], v[204:205], 0, s[76:77]
	s_mov_b32 m0, s93
	s_nop 0
	global_load_lds_dwordx4 v[184:185], off
	v_lshl_add_u64 v[184:185], v[204:205], 0, s[78:79]
	s_mov_b32 m0, s94
	s_nop 0
	global_load_lds_dwordx4 v[184:185], off
	s_waitcnt vmcnt(8)
	s_waitcnt lgkmcnt(0)
	s_setprio 1
	s_barrier
	v_mfma_i32_16x16x64_i8 v[86:89], v[132:135], v[164:167], v[86:89]
	v_mfma_i32_16x16x64_i8 v[30:33], v[140:143], v[164:167], v[30:33]
	v_mfma_i32_16x16x64_i8 v[78:81], v[132:135], v[172:175], v[78:81]
	v_mfma_i32_16x16x64_i8 v[22:25], v[140:143], v[172:175], v[22:25]
	v_mfma_i32_16x16x64_i8 v[70:73], v[132:135], v[180:183], v[70:73]
	v_mfma_i32_16x16x64_i8 v[14:17], v[140:143], v[180:183], v[14:17]
	v_mfma_i32_16x16x64_i8 v[62:65], v[132:135], v[196:199], v[62:65]
	v_mfma_i32_16x16x64_i8 v[2:5], v[140:143], v[196:199], v[2:5]
	v_mfma_i32_16x16x64_i8 v[86:89], v[136:139], v[168:171], v[86:89]
	v_mfma_i32_16x16x64_i8 v[30:33], v[144:147], v[168:171], v[30:33]
	v_mfma_i32_16x16x64_i8 v[78:81], v[136:139], v[176:179], v[78:81]
	v_mfma_i32_16x16x64_i8 v[22:25], v[144:147], v[176:179], v[22:25]
	v_mfma_i32_16x16x64_i8 v[70:73], v[136:139], v[190:193], v[70:73]
	v_mfma_i32_16x16x64_i8 v[14:17], v[144:147], v[190:193], v[14:17]
	v_mfma_i32_16x16x64_i8 v[62:65], v[136:139], v[200:203], v[62:65]
	v_mfma_i32_16x16x64_i8 v[2:5], v[144:147], v[200:203], v[2:5]
	v_mfma_i32_16x16x64_i8 v[66:69], v[148:151], v[164:167], v[66:69]
	v_mfma_i32_16x16x64_i8 v[26:29], v[156:159], v[164:167], v[26:29]
	v_mfma_i32_16x16x64_i8 v[58:61], v[148:151], v[172:175], v[58:61]
	v_mfma_i32_16x16x64_i8 v[18:21], v[156:159], v[172:175], v[18:21]
	v_mfma_i32_16x16x64_i8 v[54:57], v[148:151], v[180:183], v[54:57]
	v_mfma_i32_16x16x64_i8 v[10:13], v[156:159], v[180:183], v[10:13]
	v_mfma_i32_16x16x64_i8 v[50:53], v[148:151], v[196:199], v[50:53]
	v_mfma_i32_16x16x64_i8 v[6:9], v[156:159], v[196:199], v[6:9]
	v_mfma_i32_16x16x64_i8 v[66:69], v[152:155], v[168:171], v[66:69]
	v_mfma_i32_16x16x64_i8 v[26:29], v[160:163], v[168:171], v[26:29]
	v_mfma_i32_16x16x64_i8 v[58:61], v[152:155], v[176:179], v[58:61]
	v_mfma_i32_16x16x64_i8 v[18:21], v[160:163], v[176:179], v[18:21]
	v_mfma_i32_16x16x64_i8 v[54:57], v[152:155], v[190:193], v[54:57]
	v_mfma_i32_16x16x64_i8 v[10:13], v[160:163], v[190:193], v[10:13]
	v_mfma_i32_16x16x64_i8 v[50:53], v[152:155], v[200:203], v[50:53]
	v_mfma_i32_16x16x64_i8 v[6:9], v[160:163], v[200:203], v[6:9]
	s_barrier
	s_setprio 0
	s_add_i32 s14, s14, 2
	s_add_u32 s16, s16, 0x8000
	s_addc_u32 s17, s17, 0
	s_cmp_gt_u32 s14, 13
	s_mov_b64 s[28:29], s[30:31]
	.p2align 6

;     __device__ __forceinline__ bool next(int i, Unit& u) const { const int off = i * H + (r >> 1); if (off >= 8 * nN) return false; u.pm = 16 * g + 8 * (r & 1) + (off & 7); u.pn = off >> 3; return true; }
; #define PG8_STAGE(bufoff, gbase, unused) do { _Pragma("unroll") for (int _i = 0; _i < 2; ++_i) \
;         __builtin_amdgcn_global_load_lds((const unsigned*)((const char*)(gbase) + voff + _i * 8192), (LAS unsigned*)(lds + (bufoff) + ldsw + _i * 8192), 16, 0, 0); } while (0)
; #define PG8_LDA(dst, b, h) do { _Pragma("unroll") for (int m = 0; m < 4; ++m) _Pragma("unroll") for (int k = 0; k < 2; ++k) dst[m][k] = *(const LAS bf16x8*)(lds + PG8_SA(b, h) + aoff + m * 2048 + (FP8 ? k * 16 : k * 1024)); } while (0)
; #define PG8_LDB(dst, b, h) do { _Pragma("unroll") for (int n = 0; n < 2; ++n) _Pragma("unroll") for (int k = 0; k < 2; ++k) dst[n][k] = *(const LAS bf16x8*)(lds + PG8_SB(b, h) + boff + n * 2048 + (FP8 ? k * 16 : k * 1024)); } while (0)
; #define PG8_BAR __builtin_amdgcn_s_barrier()
; template <class Epi, class Sched, bool ALIGN_EPI, bool SP2, int MODE  >
; __device__ __forceinline__ void gemm_phase(LAS unsigned char* lds, const Gemm g, const Sched S, const Epi E, unsigned long long& probe_acc, int epi_id, int wv) {
;     ...
;         const bool has_next = S.next(ui + 1, nxt);
;         const char* nA = has_next ? (const char*)g.A + (size_t)nxt.pm * tA + (g.gt ? (size_t)(nxt.pn / g.gt) * gK2 : 0) : cA; const char* nB = has_next ? (const char*)g.Bt + (size_t)nxt.pn * tB : cB;
;         for (int t = 0; t < nt; t += 2) {
;             const bool last = (t == nt - 2);
;             const char* a1 = cA + (size_t)(t + 1) * kstep;
;             const char* a2 = last ? nA : cA + (size_t)(t + 2) * kstep; const char* b2 = last ? nB : cB + (size_t)(t + 2) * kstep;
;             const char* a3 = a2 + kstep; const char* b3 = b2 + kstep;
;             if constexpr (SP2) {
;             PG8_LDB(B0, 0, 0); PG8_LDB(B1, 0, 1); PG8_SCHED; PG8_LDA(At, 0, 0); PG8_STAGE(PG8_SA(1, 1), a1 + hA, voffA);
;             PG8_WAIT_V(8); PG8_WAIT_L(0); PG8_BAR; PG8_MMA(0, 0, At, B0); PG8_MMA(0, 1, At, B1); PG8_BAR; PG8_SCHED;
;             PG8_LDA(At, 0, 1); PG8_STAGE(PG8_SB(0, 0), b2, voffB); PG8_STAGE(PG8_SB(0, 1), b2 + hB, voffB); PG8_STAGE(PG8_SA(0, 0), a2, voffA);
;             PG8_WAIT_V(8); PG8_WAIT_L(0); PG8_BAR; PG8_MMA(1, 0, At, B0); PG8_MMA(1, 1, At, B1); PG8_BAR; PG8_SCHED;
.LBB0_364:
	s_mov_b64 s[20:21], s[4:5]
	s_add_i32 s84, s84, 1
	v_readlane_b32 s4, v254, 6
	s_mul_i32 s4, s84, s4
	v_readlane_b32 s5, v254, 35
	s_add_i32 s4, s4, s5
	s_cmpk_lt_i32 s4, 0xc0
	s_mov_b64 s[18:19], s[10:11]
	s_cselect_b64 s[16:17], -1, 0
	s_and_b32 s5, s4, 7
	v_readlane_b32 s10, v254, 18
	s_mov_b32 s8, s87
	s_mov_b32 s9, s86
	s_mov_b32 s88, s87
	s_mov_b32 s89, s86
	s_or_b32 s87, s5, s10
	s_ashr_i32 s86, s4, 3
	s_and_b64 s[4:5], s[16:17], exec
	s_cselect_b32 s10, s87, s8
	s_cselect_b32 s4, s86, s9
	s_ashr_i32 s11, s10, 31
	s_lshl_b64 s[10:11], s[10:11], 20
	s_add_u32 s10, s58, s10
	s_addc_u32 s11, s59, s11
	s_and_b64 s[90:91], s[16:17], exec
	s_cselect_b32 s46, s11, s19
	s_cselect_b32 s90, s10, s18
	s_ashr_i32 s5, s4, 31
	s_lshl_b64 s[4:5], s[4:5], 20
	s_add_u32 s4, s0, s4
	s_addc_u32 s5, s1, s5
	s_and_b64 s[92:93], s[16:17], exec
	s_cselect_b32 s91, s5, s21
	s_cselect_b32 s92, s4, s20
	s_add_u32 s93, s20, 0x8000
	s_addc_u32 s94, s21, 0
	s_mov_b32 s95, -2
	v_add_u32_e32 v0, s2, v166
	s_waitcnt vmcnt(0)
	ds_read_b128 v[130:133], v0
	ds_read_b128 v[134:137], v0 offset:1024
	ds_read_b128 v[138:141], v0 offset:2048
	ds_read_b128 v[142:145], v0 offset:3072
	v_add_u32_e32 v0, s23, v166
	ds_read_b128 v[146:149], v0
	ds_read_b128 v[150:153], v0 offset:1024
	s_waitcnt lgkmcnt(0)
	ds_read_b128 v[156:159], v0 offset:2048
	ds_read_b128 v[160:163], v0 offset:3072
	s_add_u32 s20, s18, 0x8000
	s_addc_u32 s21, s19, 0
	s_cmp_eq_u32 s95, 28
	s_cselect_b32 vcc_hi, s46, s21
	s_cselect_b32 vcc_lo, s90, s20
	s_cselect_b32 s9, s91, s94
	s_cselect_b32 s8, s92, s93
	v_lshl_add_u64 v[184:185], s[18:19], 0, v[154:155]
	v_lshl_add_u64 v[204:205], v[184:185], 0, s[52:53]
	s_add_i32 m0, s26, 0xc000
	ds_read_b128 v[168:171], v167
	ds_read_b128 v[172:175], v167 offset:1024
	ds_read_b128 v[176:179], v167 offset:2048
	ds_read_b128 v[180:183], v167 offset:3072
	ds_read_b128 v[188:191], v167 offset:4096
	ds_read_b128 v[192:195], v167 offset:5120
	ds_read_b128 v[196:199], v167 offset:6144
	ds_read_b128 v[200:203], v167 offset:7168
	global_load_lds_dwordx4 v[204:205], off
	v_lshl_add_u64 v[184:185], v[184:185], 0, s[54:55]
	s_add_i32 m0, s26, 0xe000
	s_nop 0
	global_load_lds_dwordx4 v[184:185], off
	s_waitcnt vmcnt(8)
	s_waitcnt lgkmcnt(0)
	s_setprio 1
	s_barrier
	v_mfma_f32_16x16x32_bf16 v[126:129], v[130:133], v[168:171], 0
	v_mfma_f32_16x16x32_bf16 v[122:125], v[138:141], v[168:171], 0
	v_mfma_f32_16x16x32_bf16 v[110:113], v[130:133], v[176:179], 0
	v_mfma_f32_16x16x32_bf16 v[106:109], v[138:141], v[176:179], 0
	v_mfma_f32_16x16x32_bf16 v[94:97], v[130:133], v[188:191], 0
	v_mfma_f32_16x16x32_bf16 v[90:93], v[138:141], v[188:191], 0
	v_mfma_f32_16x16x32_bf16 v[78:81], v[130:133], v[196:199], 0
	v_mfma_f32_16x16x32_bf16 v[74:77], v[138:141], v[196:199], 0
	v_mfma_f32_16x16x32_bf16 v[126:129], v[134:137], v[172:175], v[126:129]
	v_mfma_f32_16x16x32_bf16 v[122:125], v[142:145], v[172:175], v[122:125]
	v_mfma_f32_16x16x32_bf16 v[110:113], v[134:137], v[180:183], v[110:113]
	v_mfma_f32_16x16x32_bf16 v[106:109], v[142:145], v[180:183], v[106:109]
	v_mfma_f32_16x16x32_bf16 v[94:97], v[134:137], v[192:195], v[94:97]
	v_mfma_f32_16x16x32_bf16 v[90:93], v[142:145], v[192:195], v[90:93]
	v_mfma_f32_16x16x32_bf16 v[78:81], v[134:137], v[200:203], v[78:81]
	v_mfma_f32_16x16x32_bf16 v[74:77], v[142:145], v[200:203], v[74:77]
	v_mfma_f32_16x16x32_bf16 v[118:121], v[146:149], v[168:171], 0
	v_mfma_f32_16x16x32_bf16 v[114:117], v[156:159], v[168:171], 0
	v_mfma_f32_16x16x32_bf16 v[102:105], v[146:149], v[176:179], 0
	v_mfma_f32_16x16x32_bf16 v[98:101], v[156:159], v[176:179], 0
	v_mfma_f32_16x16x32_bf16 v[86:89], v[146:149], v[188:191], 0
	v_mfma_f32_16x16x32_bf16 v[82:85], v[156:159], v[188:191], 0
	v_mfma_f32_16x16x32_bf16 v[70:73], v[146:149], v[196:199], 0
	v_mfma_f32_16x16x32_bf16 v[66:69], v[156:159], v[196:199], 0
	v_mfma_f32_16x16x32_bf16 v[118:121], v[150:153], v[172:175], v[118:121]
	v_mfma_f32_16x16x32_bf16 v[114:117], v[160:163], v[172:175], v[114:117]
	v_mfma_f32_16x16x32_bf16 v[102:105], v[150:153], v[180:183], v[102:105]
	v_mfma_f32_16x16x32_bf16 v[98:101], v[160:163], v[180:183], v[98:101]
	v_mfma_f32_16x16x32_bf16 v[86:89], v[150:153], v[192:195], v[86:89]
	v_mfma_f32_16x16x32_bf16 v[82:85], v[160:163], v[192:195], v[82:85]
	v_mfma_f32_16x16x32_bf16 v[70:73], v[150:153], v[200:203], v[70:73]
	v_mfma_f32_16x16x32_bf16 v[66:69], v[160:163], v[200:203], v[66:69]
	s_barrier
	s_setprio 0
	s_mov_b32 m0, s3
	v_lshl_add_u64 v[184:185], s[8:9], 0, v[154:155]
	ds_read_b128 v[168:171], v167 offset:16384
	ds_read_b128 v[172:175], v167 offset:17408
	ds_read_b128 v[176:179], v167 offset:18432
	ds_read_b128 v[180:183], v167 offset:19456
	ds_read_b128 v[188:191], v167 offset:20480
	ds_read_b128 v[192:195], v167 offset:21504
	ds_read_b128 v[196:199], v167 offset:22528
	ds_read_b128 v[200:203], v167 offset:23552
	global_load_lds_dwordx4 v[184:185], off
	v_lshl_add_u64 v[204:205], v[184:185], 0, s[70:71]
	s_mov_b32 m0, s22
	s_nop 0
	global_load_lds_dwordx4 v[204:205], off
	v_lshl_add_u64 v[204:205], v[184:185], 0, s[96:97]
	s_mov_b32 m0, s24
	s_nop 0
	global_load_lds_dwordx4 v[204:205], off
	v_lshl_add_u64 v[204:205], v[184:185], 0, s[60:61]
	s_mov_b32 m0, s25
	s_nop 0
	global_load_lds_dwordx4 v[204:205], off
	v_lshl_add_u64 v[204:205], vcc, 0, v[154:155]
	s_mov_b32 m0, s26
	v_lshl_add_u64 v[206:207], v[204:205], 0, s[70:71]
	global_load_lds_dwordx4 v[204:205], off
	s_mov_b32 m0, s27
	s_nop 0
	global_load_lds_dwordx4 v[206:207], off
	s_waitcnt vmcnt(8)
	s_waitcnt lgkmcnt(0)
	s_setprio 1
	s_barrier
; #define PG8_STAGE(bufoff, gbase, unused) do { _Pragma("unroll") for (int _i = 0; _i < 2; ++_i) \
;         __builtin_amdgcn_global_load_lds((const unsigned*)((const char*)(gbase) + voff + _i * 8192), (LAS unsigned*)(lds + (bufoff) + ldsw + _i * 8192), 16, 0, 0); } while (0)
; #define PG8_LDA(dst, b, h) do { _Pragma("unroll") for (int m = 0; m < 4; ++m) _Pragma("unroll") for (int k = 0; k < 2; ++k) dst[m][k] = *(const LAS bf16x8*)(lds + PG8_SA(b, h) + aoff + m * 2048 + (FP8 ? k * 16 : k * 1024)); } while (0)
; #define PG8_LDB(dst, b, h) do { _Pragma("unroll") for (int n = 0; n < 2; ++n) _Pragma("unroll") for (int k = 0; k < 2; ++k) dst[n][k] = *(const LAS bf16x8*)(lds + PG8_SB(b, h) + boff + n * 2048 + (FP8 ? k * 16 : k * 1024)); } while (0)
; #define PG8_WAIT_V(n) asm volatile("s_waitcnt vmcnt(" #n ")" ::: "memory")
; #define PG8_WAIT_L(n) asm volatile("s_waitcnt lgkmcnt(" #n ")" ::: "memory")
; #define PG8_BAR __builtin_amdgcn_s_barrier()
; #define PG8_SCHED __builtin_amdgcn_sched_barrier(0)
; template <class Epi, class Sched, bool ALIGN_EPI, bool SP2, int MODE  >
; __device__ __forceinline__ void gemm_phase(LAS unsigned char* lds, const Gemm g, const Sched S, const Epi E, unsigned long long& probe_acc, int epi_id, int wv) {
;     ...
;             PG8_WAIT_V(8); PG8_WAIT_L(0); PG8_BAR; PG8_MMA(1, 0, At, B0); PG8_MMA(1, 1, At, B1); PG8_BAR; PG8_SCHED;
;             PG8_LDB(B0, 1, 0); PG8_LDB(B1, 1, 1); PG8_SCHED; PG8_LDA(At, 1, 0); PG8_STAGE(PG8_SA(0, 1), a2 + hA, voffA);
;             PG8_WAIT_V(8); PG8_WAIT_L(0); PG8_BAR; PG8_MMA(0, 0, At, B0); PG8_MMA(0, 1, At, B1); PG8_BAR; PG8_SCHED;
	v_mfma_f32_16x16x32_bf16 v[62:65], v[130:133], v[168:171], 0
	v_mfma_f32_16x16x32_bf16 v[58:61], v[138:141], v[168:171], 0
	v_mfma_f32_16x16x32_bf16 v[46:49], v[130:133], v[176:179], 0
	v_mfma_f32_16x16x32_bf16 v[42:45], v[138:141], v[176:179], 0
	v_mfma_f32_16x16x32_bf16 v[30:33], v[130:133], v[188:191], 0
	v_mfma_f32_16x16x32_bf16 v[26:29], v[138:141], v[188:191], 0
	v_mfma_f32_16x16x32_bf16 v[14:17], v[130:133], v[196:199], 0
	v_mfma_f32_16x16x32_bf16 v[10:13], v[138:141], v[196:199], 0
	v_mfma_f32_16x16x32_bf16 v[62:65], v[134:137], v[172:175], v[62:65]
	v_mfma_f32_16x16x32_bf16 v[58:61], v[142:145], v[172:175], v[58:61]
	v_mfma_f32_16x16x32_bf16 v[46:49], v[134:137], v[180:183], v[46:49]
	v_mfma_f32_16x16x32_bf16 v[42:45], v[142:145], v[180:183], v[42:45]
	v_mfma_f32_16x16x32_bf16 v[30:33], v[134:137], v[192:195], v[30:33]
	v_mfma_f32_16x16x32_bf16 v[26:29], v[142:145], v[192:195], v[26:29]
	v_mfma_f32_16x16x32_bf16 v[14:17], v[134:137], v[200:203], v[14:17]
	v_mfma_f32_16x16x32_bf16 v[10:13], v[142:145], v[200:203], v[10:13]
	v_mfma_f32_16x16x32_bf16 v[54:57], v[146:149], v[168:171], 0
	v_mfma_f32_16x16x32_bf16 v[50:53], v[156:159], v[168:171], 0
	v_mfma_f32_16x16x32_bf16 v[38:41], v[146:149], v[176:179], 0
	v_mfma_f32_16x16x32_bf16 v[34:37], v[156:159], v[176:179], 0
	v_mfma_f32_16x16x32_bf16 v[22:25], v[146:149], v[188:191], 0
	v_mfma_f32_16x16x32_bf16 v[18:21], v[156:159], v[188:191], 0
	v_mfma_f32_16x16x32_bf16 v[6:9], v[146:149], v[196:199], 0
	v_mfma_f32_16x16x32_bf16 v[2:5], v[156:159], v[196:199], 0
	v_mfma_f32_16x16x32_bf16 v[54:57], v[150:153], v[172:175], v[54:57]
	v_mfma_f32_16x16x32_bf16 v[50:53], v[160:163], v[172:175], v[50:53]
	v_mfma_f32_16x16x32_bf16 v[38:41], v[150:153], v[180:183], v[38:41]
	v_mfma_f32_16x16x32_bf16 v[34:37], v[160:163], v[180:183], v[34:37]
	v_mfma_f32_16x16x32_bf16 v[22:25], v[150:153], v[192:195], v[22:25]
	v_mfma_f32_16x16x32_bf16 v[18:21], v[160:163], v[192:195], v[18:21]
	v_mfma_f32_16x16x32_bf16 v[6:9], v[150:153], v[200:203], v[6:9]
	v_mfma_f32_16x16x32_bf16 v[2:5], v[160:163], v[200:203], v[2:5]
	s_barrier
	s_setprio 0
	v_add_u32_e32 v0, s31, v166
	ds_read_b128 v[130:133], v0
	ds_read_b128 v[134:137], v0 offset:1024
	ds_read_b128 v[138:141], v0 offset:2048
	ds_read_b128 v[142:145], v0 offset:3072
	v_add_u32_e32 v0, s39, v166
	ds_read_b128 v[146:149], v0
	ds_read_b128 v[150:153], v0 offset:1024
	ds_read_b128 v[156:159], v0 offset:2048
	ds_read_b128 v[160:163], v0 offset:3072
	s_mov_b32 m0, s28
	v_lshl_add_u64 v[206:207], v[204:205], 0, s[96:97]
	ds_read_b128 v[168:171], v167 offset:32768
	ds_read_b128 v[172:175], v167 offset:33792
	ds_read_b128 v[176:179], v167 offset:34816
	ds_read_b128 v[180:183], v167 offset:35840
	ds_read_b128 v[188:191], v167 offset:36864
	ds_read_b128 v[192:195], v167 offset:37888
	ds_read_b128 v[196:199], v167 offset:38912
	ds_read_b128 v[200:203], v167 offset:39936
	global_load_lds_dwordx4 v[206:207], off
	v_lshl_add_u64 v[206:207], v[204:205], 0, s[60:61]
	s_mov_b32 m0, s29
	s_nop 0
	global_load_lds_dwordx4 v[206:207], off
	s_waitcnt vmcnt(8)
	s_waitcnt lgkmcnt(0)
	s_setprio 1
	s_barrier
	v_mfma_f32_16x16x32_bf16 v[126:129], v[130:133], v[168:171], v[126:129]
	v_mfma_f32_16x16x32_bf16 v[122:125], v[138:141], v[168:171], v[122:125]
	v_mfma_f32_16x16x32_bf16 v[110:113], v[130:133], v[176:179], v[110:113]
	v_mfma_f32_16x16x32_bf16 v[106:109], v[138:141], v[176:179], v[106:109]
	v_mfma_f32_16x16x32_bf16 v[94:97], v[130:133], v[188:191], v[94:97]
	v_mfma_f32_16x16x32_bf16 v[90:93], v[138:141], v[188:191], v[90:93]
	v_mfma_f32_16x16x32_bf16 v[78:81], v[130:133], v[196:199], v[78:81]
	v_mfma_f32_16x16x32_bf16 v[74:77], v[138:141], v[196:199], v[74:77]
	v_mfma_f32_16x16x32_bf16 v[126:129], v[134:137], v[172:175], v[126:129]
	v_mfma_f32_16x16x32_bf16 v[122:125], v[142:145], v[172:175], v[122:125]
	v_mfma_f32_16x16x32_bf16 v[110:113], v[134:137], v[180:183], v[110:113]
	v_mfma_f32_16x16x32_bf16 v[106:109], v[142:145], v[180:183], v[106:109]
	v_mfma_f32_16x16x32_bf16 v[94:97], v[134:137], v[192:195], v[94:97]
	v_mfma_f32_16x16x32_bf16 v[90:93], v[142:145], v[192:195], v[90:93]
	v_mfma_f32_16x16x32_bf16 v[78:81], v[134:137], v[200:203], v[78:81]
	v_mfma_f32_16x16x32_bf16 v[74:77], v[142:145], v[200:203], v[74:77]
	v_mfma_f32_16x16x32_bf16 v[118:121], v[146:149], v[168:171], v[118:121]
	v_mfma_f32_16x16x32_bf16 v[114:117], v[156:159], v[168:171], v[114:117]
	v_mfma_f32_16x16x32_bf16 v[102:105], v[146:149], v[176:179], v[102:105]
	v_mfma_f32_16x16x32_bf16 v[98:101], v[156:159], v[176:179], v[98:101]
	v_mfma_f32_16x16x32_bf16 v[86:89], v[146:149], v[188:191], v[86:89]
	v_mfma_f32_16x16x32_bf16 v[82:85], v[156:159], v[188:191], v[82:85]
	v_mfma_f32_16x16x32_bf16 v[70:73], v[146:149], v[196:199], v[70:73]
	v_mfma_f32_16x16x32_bf16 v[66:69], v[156:159], v[196:199], v[66:69]
	v_mfma_f32_16x16x32_bf16 v[118:121], v[150:153], v[172:175], v[118:121]
	v_mfma_f32_16x16x32_bf16 v[114:117], v[160:163], v[172:175], v[114:117]
	v_mfma_f32_16x16x32_bf16 v[102:105], v[150:153], v[180:183], v[102:105]
	v_mfma_f32_16x16x32_bf16 v[98:101], v[160:163], v[180:183], v[98:101]
	v_mfma_f32_16x16x32_bf16 v[86:89], v[150:153], v[192:195], v[86:89]
	v_mfma_f32_16x16x32_bf16 v[82:85], v[160:163], v[192:195], v[82:85]
	v_mfma_f32_16x16x32_bf16 v[70:73], v[150:153], v[200:203], v[70:73]
	v_mfma_f32_16x16x32_bf16 v[66:69], v[160:163], v[200:203], v[66:69]
	s_barrier
; #define PG8_STAGE(bufoff, gbase, unused) do { _Pragma("unroll") for (int _i = 0; _i < 2; ++_i) \
;         __builtin_amdgcn_global_load_lds((const unsigned*)((const char*)(gbase) + voff + _i * 8192), (LAS unsigned*)(lds + (bufoff) + ldsw + _i * 8192), 16, 0, 0); } while (0)
; #define PG8_LDA(dst, b, h) do { _Pragma("unroll") for (int m = 0; m < 4; ++m) _Pragma("unroll") for (int k = 0; k < 2; ++k) dst[m][k] = *(const LAS bf16x8*)(lds + PG8_SA(b, h) + aoff + m * 2048 + (FP8 ? k * 16 : k * 1024)); } while (0)
; #define PG8_WAIT_V(n) asm volatile("s_waitcnt vmcnt(" #n ")" ::: "memory")
; #define PG8_WAIT_L(n) asm volatile("s_waitcnt lgkmcnt(" #n ")" ::: "memory")
; #define PG8_BAR __builtin_amdgcn_s_barrier()
; #define PG8_SCHED __builtin_amdgcn_sched_barrier(0)
; template <class Epi, class Sched, bool ALIGN_EPI, bool SP2, int MODE  >
; __device__ __forceinline__ void gemm_phase(LAS unsigned char* lds, const Gemm g, const Sched S, const Epi E, unsigned long long& probe_acc, int epi_id, int wv) {
;     ...
;             PG8_WAIT_V(8); PG8_WAIT_L(0); PG8_BAR; PG8_MMA(0, 0, At, B0); PG8_MMA(0, 1, At, B1); PG8_BAR; PG8_SCHED;
;             PG8_LDA(At, 1, 1); PG8_STAGE(PG8_SB(1, 0), b3, voffB); PG8_STAGE(PG8_SB(1, 1), b3 + hB, voffB); PG8_STAGE(PG8_SA(1, 0), a3, voffA);
;             PG8_WAIT_V(8); PG8_WAIT_L(0); PG8_BAR; PG8_MMA(1, 0, At, B0); PG8_MMA(1, 1, At, B1); PG8_BAR; PG8_SCHED;
	s_setprio 0
	s_mov_b32 m0, s34
	v_lshl_add_u64 v[206:207], v[184:185], 0, s[76:77]
	ds_read_b128 v[168:171], v167 offset:49152
	ds_read_b128 v[172:175], v167 offset:50176
	ds_read_b128 v[176:179], v167 offset:51200
	ds_read_b128 v[180:183], v167 offset:52224
	ds_read_b128 v[188:191], v167 offset:53248
	ds_read_b128 v[192:195], v167 offset:54272
	ds_read_b128 v[196:199], v167 offset:55296
	ds_read_b128 v[200:203], v167 offset:56320
	global_load_lds_dwordx4 v[206:207], off
	v_lshl_add_u64 v[206:207], v[184:185], 0, s[78:79]
	s_mov_b32 m0, s35
	s_nop 0
	global_load_lds_dwordx4 v[206:207], off
	v_lshl_add_u64 v[206:207], v[184:185], 0, s[52:53]
	s_mov_b32 m0, s40
	v_lshl_add_u64 v[184:185], v[184:185], 0, s[54:55]
	global_load_lds_dwordx4 v[206:207], off
	s_mov_b32 m0, s41
	s_nop 0
	global_load_lds_dwordx4 v[184:185], off
	v_lshl_add_u64 v[184:185], v[204:205], 0, s[76:77]
	s_mov_b32 m0, s36
	s_nop 0
	global_load_lds_dwordx4 v[184:185], off
	v_lshl_add_u64 v[184:185], v[204:205], 0, s[78:79]
	s_mov_b32 m0, s37
	s_nop 0
	global_load_lds_dwordx4 v[184:185], off
	s_waitcnt vmcnt(8)
	s_waitcnt lgkmcnt(0)
	s_setprio 1
	s_barrier
	v_mfma_f32_16x16x32_bf16 v[62:65], v[130:133], v[168:171], v[62:65]
	v_mfma_f32_16x16x32_bf16 v[58:61], v[138:141], v[168:171], v[58:61]
	v_mfma_f32_16x16x32_bf16 v[46:49], v[130:133], v[176:179], v[46:49]
	v_mfma_f32_16x16x32_bf16 v[42:45], v[138:141], v[176:179], v[42:45]
	v_mfma_f32_16x16x32_bf16 v[30:33], v[130:133], v[188:191], v[30:33]
	v_mfma_f32_16x16x32_bf16 v[26:29], v[138:141], v[188:191], v[26:29]
	v_mfma_f32_16x16x32_bf16 v[14:17], v[130:133], v[196:199], v[14:17]
	v_mfma_f32_16x16x32_bf16 v[10:13], v[138:141], v[196:199], v[10:13]
	v_mfma_f32_16x16x32_bf16 v[62:65], v[134:137], v[172:175], v[62:65]
	v_mfma_f32_16x16x32_bf16 v[58:61], v[142:145], v[172:175], v[58:61]
	v_mfma_f32_16x16x32_bf16 v[46:49], v[134:137], v[180:183], v[46:49]
	v_mfma_f32_16x16x32_bf16 v[42:45], v[142:145], v[180:183], v[42:45]
	v_mfma_f32_16x16x32_bf16 v[30:33], v[134:137], v[192:195], v[30:33]
	v_mfma_f32_16x16x32_bf16 v[26:29], v[142:145], v[192:195], v[26:29]
	v_mfma_f32_16x16x32_bf16 v[14:17], v[134:137], v[200:203], v[14:17]
	v_mfma_f32_16x16x32_bf16 v[10:13], v[142:145], v[200:203], v[10:13]
	v_mfma_f32_16x16x32_bf16 v[54:57], v[146:149], v[168:171], v[54:57]
	v_mfma_f32_16x16x32_bf16 v[50:53], v[156:159], v[168:171], v[50:53]
	v_mfma_f32_16x16x32_bf16 v[38:41], v[146:149], v[176:179], v[38:41]
	v_mfma_f32_16x16x32_bf16 v[34:37], v[156:159], v[176:179], v[34:37]
	v_mfma_f32_16x16x32_bf16 v[22:25], v[146:149], v[188:191], v[22:25]
	v_mfma_f32_16x16x32_bf16 v[18:21], v[156:159], v[188:191], v[18:21]
	v_mfma_f32_16x16x32_bf16 v[6:9], v[146:149], v[196:199], v[6:9]
	v_mfma_f32_16x16x32_bf16 v[2:5], v[156:159], v[196:199], v[2:5]
	v_mfma_f32_16x16x32_bf16 v[54:57], v[150:153], v[172:175], v[54:57]
	v_mfma_f32_16x16x32_bf16 v[50:53], v[160:163], v[172:175], v[50:53]
	v_mfma_f32_16x16x32_bf16 v[38:41], v[150:153], v[180:183], v[38:41]
	v_mfma_f32_16x16x32_bf16 v[34:37], v[160:163], v[180:183], v[34:37]
	v_mfma_f32_16x16x32_bf16 v[22:25], v[150:153], v[192:195], v[22:25]
	v_mfma_f32_16x16x32_bf16 v[18:21], v[160:163], v[192:195], v[18:21]
	v_mfma_f32_16x16x32_bf16 v[6:9], v[150:153], v[200:203], v[6:9]
	v_mfma_f32_16x16x32_bf16 v[2:5], v[160:163], v[200:203], v[2:5]
	s_barrier
	s_setprio 0
	s_add_i32 s95, s95, 2
	s_add_u32 s93, s93, 0x8000
	s_addc_u32 s94, s94, 0
	s_cmp_gt_u32 s95, 29
	s_mov_b64 s[18:19], s[20:21]
	.p2align 6

; #define PG8_STAGE(bufoff, gbase, unused) do { _Pragma("unroll") for (int _i = 0; _i < 2; ++_i) \
;         __builtin_amdgcn_global_load_lds((const unsigned*)((const char*)(gbase) + voff + _i * 8192), (LAS unsigned*)(lds + (bufoff) + ldsw + _i * 8192), 16, 0, 0); } while (0)
; #define PG8_LDA(dst, b, h) do { _Pragma("unroll") for (int m = 0; m < 4; ++m) _Pragma("unroll") for (int k = 0; k < 2; ++k) dst[m][k] = *(const LAS bf16x8*)(lds + PG8_SA(b, h) + aoff + m * 2048 + (FP8 ? k * 16 : k * 1024)); } while (0)
; #define PG8_LDB(dst, b, h) do { _Pragma("unroll") for (int n = 0; n < 2; ++n) _Pragma("unroll") for (int k = 0; k < 2; ++k) dst[n][k] = *(const LAS bf16x8*)(lds + PG8_SB(b, h) + boff + n * 2048 + (FP8 ? k * 16 : k * 1024)); } while (0)
; #define PG8_WAIT_V(n) asm volatile("s_waitcnt vmcnt(" #n ")" ::: "memory")
; #define PG8_WAIT_L(n) asm volatile("s_waitcnt lgkmcnt(" #n ")" ::: "memory")
; #define PG8_BAR __builtin_amdgcn_s_barrier()
; #define PG8_SCHED __builtin_amdgcn_sched_barrier(0)
; template <class Epi, class Sched, bool ALIGN_EPI, bool SP2, int MODE  >
; __device__ __forceinline__ void gemm_phase(LAS unsigned char* lds, const Gemm g, const Sched S, const Epi E, unsigned long long& probe_acc, int epi_id, int wv) {
;     ...
;         for (int t = 0; t < nt; t += 2) {
;             const bool last = (t == nt - 2);
;             const char* a1 = cA + (size_t)(t + 1) * kstep;
;             const char* a2 = last ? nA : cA + (size_t)(t + 2) * kstep; const char* b2 = last ? nB : cB + (size_t)(t + 2) * kstep;
;             const char* a3 = a2 + kstep; const char* b3 = b2 + kstep;
;             if constexpr (SP2) {
;             PG8_LDB(B0, 0, 0); PG8_LDB(B1, 0, 1); PG8_SCHED; PG8_LDA(At, 0, 0); PG8_STAGE(PG8_SA(1, 1), a1 + hA, voffA);
;             PG8_WAIT_V(8); PG8_WAIT_L(0); PG8_BAR; PG8_MMA(0, 0, At, B0); PG8_MMA(0, 1, At, B1); PG8_BAR; PG8_SCHED;
;             PG8_LDA(At, 0, 1); PG8_STAGE(PG8_SB(0, 0), b2, voffB); PG8_STAGE(PG8_SB(0, 1), b2 + hB, voffB); PG8_STAGE(PG8_SA(0, 0), a2, voffA);
;             PG8_WAIT_V(8); PG8_WAIT_L(0); PG8_BAR; PG8_MMA(1, 0, At, B0); PG8_MMA(1, 1, At, B1); PG8_BAR; PG8_SCHED;
.LBB0_673:
	s_add_u32 s10, s4, 0x8000
	s_addc_u32 s11, s5, 0
	s_add_u32 s4, s6, 0x8000
	s_addc_u32 s5, s7, 0
	s_mov_b32 s6, 0
	s_waitcnt lgkmcnt(0)
	s_waitcnt vmcnt(0)
	v_add_u32_e32 v142, s15, v193
	v_add_u32_e32 v156, s39, v193
	ds_read_b128 v[130:133], v142
	ds_read_b128 v[134:137], v142 offset:1024
	ds_read_b128 v[138:141], v142 offset:2048
	ds_read_b128 v[142:145], v142 offset:3072
	ds_read_b128 v[146:149], v156
	ds_read_b128 v[150:153], v156 offset:1024
	ds_read_b128 v[158:161], v156 offset:2048
	ds_read_b128 v[162:165], v156 offset:3072
	s_add_i32 s40, s6, 2
	s_cmp_eq_u32 s93, s6
	s_cselect_b32 s6, s34, s10
	s_cselect_b32 s9, s87, s5
	s_cselect_b32 s8, s86, s4
	s_cselect_b32 s7, s35, s11
	s_movk_i32 vcc_lo, 0xc000
	v_lshl_add_u64 v[190:191], s[4:5], 0, v[154:155]
	s_mov_b32 vcc_hi, -1
	v_lshl_add_u64 v[196:197], v[190:191], 0, vcc
	s_movk_i32 vcc_lo, 0xe000
	s_add_i32 m0, s88, 0xc000
	s_mov_b32 vcc_hi, -1
	ds_read_b128 v[166:169], v194
	ds_read_b128 v[170:173], v194 offset:1024
	ds_read_b128 v[174:177], v194 offset:2048
	ds_read_b128 v[178:181], v194 offset:3072
	ds_read_b128 v[182:185], v194 offset:4096
	ds_read_b128 v[186:189], v194 offset:5120
	ds_read_b128 v[200:203], v194 offset:6144
	ds_read_b128 v[204:207], v194 offset:7168
	global_load_lds_dwordx4 v[196:197], off
	v_lshl_add_u64 v[190:191], v[190:191], 0, vcc
	s_add_i32 m0, s88, 0xe000
	s_nop 0
	global_load_lds_dwordx4 v[190:191], off
	s_waitcnt vmcnt(8)
	s_waitcnt lgkmcnt(0)
	s_setprio 1
	s_barrier
	v_mfma_f32_16x16x32_bf16 v[126:129], v[130:133], v[166:169], 0
	v_mfma_f32_16x16x32_bf16 v[122:125], v[138:141], v[166:169], 0
	v_mfma_f32_16x16x32_bf16 v[118:121], v[130:133], v[174:177], 0
	v_mfma_f32_16x16x32_bf16 v[114:117], v[138:141], v[174:177], 0
	v_mfma_f32_16x16x32_bf16 v[110:113], v[130:133], v[182:185], 0
	v_mfma_f32_16x16x32_bf16 v[106:109], v[138:141], v[182:185], 0
	v_mfma_f32_16x16x32_bf16 v[102:105], v[130:133], v[200:203], 0
	v_mfma_f32_16x16x32_bf16 v[98:101], v[138:141], v[200:203], 0
	v_mfma_f32_16x16x32_bf16 v[126:129], v[134:137], v[170:173], v[126:129]
	v_mfma_f32_16x16x32_bf16 v[122:125], v[142:145], v[170:173], v[122:125]
	v_mfma_f32_16x16x32_bf16 v[118:121], v[134:137], v[178:181], v[118:121]
	v_mfma_f32_16x16x32_bf16 v[114:117], v[142:145], v[178:181], v[114:117]
	v_mfma_f32_16x16x32_bf16 v[110:113], v[134:137], v[186:189], v[110:113]
	v_mfma_f32_16x16x32_bf16 v[106:109], v[142:145], v[186:189], v[106:109]
	v_mfma_f32_16x16x32_bf16 v[102:105], v[134:137], v[204:207], v[102:105]
	v_mfma_f32_16x16x32_bf16 v[98:101], v[142:145], v[204:207], v[98:101]
	v_mfma_f32_16x16x32_bf16 v[62:65], v[146:149], v[166:169], 0
	v_mfma_f32_16x16x32_bf16 v[58:61], v[158:161], v[166:169], 0
	v_mfma_f32_16x16x32_bf16 v[54:57], v[146:149], v[174:177], 0
	v_mfma_f32_16x16x32_bf16 v[50:53], v[158:161], v[174:177], 0
	v_mfma_f32_16x16x32_bf16 v[46:49], v[146:149], v[182:185], 0
	v_mfma_f32_16x16x32_bf16 v[42:45], v[158:161], v[182:185], 0
	v_mfma_f32_16x16x32_bf16 v[38:41], v[146:149], v[200:203], 0
	v_mfma_f32_16x16x32_bf16 v[34:37], v[158:161], v[200:203], 0
	v_mfma_f32_16x16x32_bf16 v[62:65], v[150:153], v[170:173], v[62:65]
	v_mfma_f32_16x16x32_bf16 v[58:61], v[162:165], v[170:173], v[58:61]
	v_mfma_f32_16x16x32_bf16 v[54:57], v[150:153], v[178:181], v[54:57]
	v_mfma_f32_16x16x32_bf16 v[50:53], v[162:165], v[178:181], v[50:53]
	v_mfma_f32_16x16x32_bf16 v[46:49], v[150:153], v[186:189], v[46:49]
	v_mfma_f32_16x16x32_bf16 v[42:45], v[162:165], v[186:189], v[42:45]
	v_mfma_f32_16x16x32_bf16 v[38:41], v[150:153], v[204:207], v[38:41]
	v_mfma_f32_16x16x32_bf16 v[34:37], v[162:165], v[204:207], v[34:37]
	s_barrier
	s_setprio 0
	s_mov_b32 m0, s26
	v_lshl_add_u64 v[190:191], s[6:7], 0, v[0:1]
	s_add_u32 vcc_lo, s6, s13
	ds_read_b128 v[166:169], v194 offset:16384
	ds_read_b128 v[170:173], v194 offset:17408
	ds_read_b128 v[174:177], v194 offset:18432
	ds_read_b128 v[178:181], v194 offset:19456
	ds_read_b128 v[182:185], v194 offset:20480
	ds_read_b128 v[186:189], v194 offset:21504
	ds_read_b128 v[200:203], v194 offset:22528
	ds_read_b128 v[204:207], v194 offset:23552
	global_load_lds_dwordx4 v[190:191], off
	v_lshl_add_u64 v[190:191], v[190:191], 0, s[70:71]
	s_mov_b32 m0, s27
	s_addc_u32 vcc_hi, s7, 0
	global_load_lds_dwordx4 v[190:191], off
	v_lshl_add_u64 v[190:191], vcc, 0, v[0:1]
	s_mov_b32 m0, s84
	s_nop 0
	global_load_lds_dwordx4 v[190:191], off
	v_lshl_add_u64 v[190:191], v[190:191], 0, s[70:71]
	s_mov_b32 m0, s85
	s_nop 0
	global_load_lds_dwordx4 v[190:191], off
	v_lshl_add_u64 v[190:191], s[8:9], 0, v[0:1]
	s_mov_b32 m0, s88
	v_lshl_add_u64 v[196:197], v[190:191], 0, s[70:71]
	global_load_lds_dwordx4 v[190:191], off
	s_mov_b32 m0, s89
	s_nop 0
	global_load_lds_dwordx4 v[196:197], off
	s_waitcnt vmcnt(8)
	s_waitcnt lgkmcnt(0)
	s_setprio 1
	s_barrier
; #define PG8_STAGE(bufoff, gbase, unused) do { _Pragma("unroll") for (int _i = 0; _i < 2; ++_i) \
;         __builtin_amdgcn_global_load_lds((const unsigned*)((const char*)(gbase) + voff + _i * 8192), (LAS unsigned*)(lds + (bufoff) + ldsw + _i * 8192), 16, 0, 0); } while (0)
; #define PG8_LDA(dst, b, h) do { _Pragma("unroll") for (int m = 0; m < 4; ++m) _Pragma("unroll") for (int k = 0; k < 2; ++k) dst[m][k] = *(const LAS bf16x8*)(lds + PG8_SA(b, h) + aoff + m * 2048 + (FP8 ? k * 16 : k * 1024)); } while (0)
; #define PG8_LDB(dst, b, h) do { _Pragma("unroll") for (int n = 0; n < 2; ++n) _Pragma("unroll") for (int k = 0; k < 2; ++k) dst[n][k] = *(const LAS bf16x8*)(lds + PG8_SB(b, h) + boff + n * 2048 + (FP8 ? k * 16 : k * 1024)); } while (0)
; #define PG8_WAIT_V(n) asm volatile("s_waitcnt vmcnt(" #n ")" ::: "memory")
; #define PG8_WAIT_L(n) asm volatile("s_waitcnt lgkmcnt(" #n ")" ::: "memory")
; #define PG8_BAR __builtin_amdgcn_s_barrier()
; #define PG8_SCHED __builtin_amdgcn_sched_barrier(0)
; template <class Epi, class Sched, bool ALIGN_EPI, bool SP2, int MODE  >
; __device__ __forceinline__ void gemm_phase(LAS unsigned char* lds, const Gemm g, const Sched S, const Epi E, unsigned long long& probe_acc, int epi_id, int wv) {
;     ...
;             PG8_WAIT_V(8); PG8_WAIT_L(0); PG8_BAR; PG8_MMA(1, 0, At, B0); PG8_MMA(1, 1, At, B1); PG8_BAR; PG8_SCHED;
;             PG8_LDB(B0, 1, 0); PG8_LDB(B1, 1, 1); PG8_SCHED; PG8_LDA(At, 1, 0); PG8_STAGE(PG8_SA(0, 1), a2 + hA, voffA);
;             PG8_WAIT_V(8); PG8_WAIT_L(0); PG8_BAR; PG8_MMA(0, 0, At, B0); PG8_MMA(0, 1, At, B1); PG8_BAR; PG8_SCHED;
	v_mfma_f32_16x16x32_bf16 v[94:97], v[130:133], v[166:169], 0
	v_mfma_f32_16x16x32_bf16 v[90:93], v[138:141], v[166:169], 0
	v_mfma_f32_16x16x32_bf16 v[86:89], v[130:133], v[174:177], 0
	v_mfma_f32_16x16x32_bf16 v[82:85], v[138:141], v[174:177], 0
	v_mfma_f32_16x16x32_bf16 v[78:81], v[130:133], v[182:185], 0
	v_mfma_f32_16x16x32_bf16 v[74:77], v[138:141], v[182:185], 0
	v_mfma_f32_16x16x32_bf16 v[70:73], v[130:133], v[200:203], 0
	v_mfma_f32_16x16x32_bf16 v[66:69], v[138:141], v[200:203], 0
	v_mfma_f32_16x16x32_bf16 v[94:97], v[134:137], v[170:173], v[94:97]
	v_mfma_f32_16x16x32_bf16 v[90:93], v[142:145], v[170:173], v[90:93]
	v_mfma_f32_16x16x32_bf16 v[86:89], v[134:137], v[178:181], v[86:89]
	v_mfma_f32_16x16x32_bf16 v[82:85], v[142:145], v[178:181], v[82:85]
	v_mfma_f32_16x16x32_bf16 v[78:81], v[134:137], v[186:189], v[78:81]
	v_mfma_f32_16x16x32_bf16 v[74:77], v[142:145], v[186:189], v[74:77]
	v_mfma_f32_16x16x32_bf16 v[70:73], v[134:137], v[204:207], v[70:73]
	v_mfma_f32_16x16x32_bf16 v[66:69], v[142:145], v[204:207], v[66:69]
	v_mfma_f32_16x16x32_bf16 v[30:33], v[146:149], v[166:169], 0
	v_mfma_f32_16x16x32_bf16 v[26:29], v[158:161], v[166:169], 0
	v_mfma_f32_16x16x32_bf16 v[22:25], v[146:149], v[174:177], 0
	v_mfma_f32_16x16x32_bf16 v[18:21], v[158:161], v[174:177], 0
	v_mfma_f32_16x16x32_bf16 v[14:17], v[146:149], v[182:185], 0
	v_mfma_f32_16x16x32_bf16 v[10:13], v[158:161], v[182:185], 0
	v_mfma_f32_16x16x32_bf16 v[6:9], v[146:149], v[200:203], 0
	v_mfma_f32_16x16x32_bf16 v[2:5], v[158:161], v[200:203], 0
	v_mfma_f32_16x16x32_bf16 v[30:33], v[150:153], v[170:173], v[30:33]
	v_mfma_f32_16x16x32_bf16 v[26:29], v[162:165], v[170:173], v[26:29]
	v_mfma_f32_16x16x32_bf16 v[22:25], v[150:153], v[178:181], v[22:25]
	v_mfma_f32_16x16x32_bf16 v[18:21], v[162:165], v[178:181], v[18:21]
	v_mfma_f32_16x16x32_bf16 v[14:17], v[150:153], v[186:189], v[14:17]
	v_mfma_f32_16x16x32_bf16 v[10:13], v[162:165], v[186:189], v[10:13]
	v_mfma_f32_16x16x32_bf16 v[6:9], v[150:153], v[204:207], v[6:9]
	v_mfma_f32_16x16x32_bf16 v[2:5], v[162:165], v[204:207], v[2:5]
	s_barrier
	s_setprio 0
	v_add_u32_e32 v142, s28, v193
	v_add_u32_e32 v156, s94, v193
	ds_read_b128 v[130:133], v142
	ds_read_b128 v[134:137], v142 offset:1024
	ds_read_b128 v[138:141], v142 offset:2048
	ds_read_b128 v[142:145], v142 offset:3072
	ds_read_b128 v[146:149], v156
	ds_read_b128 v[150:153], v156 offset:1024
	ds_read_b128 v[158:161], v156 offset:2048
	ds_read_b128 v[162:165], v156 offset:3072
	s_add_u32 s8, s8, s36
	s_addc_u32 s9, s9, 0
	s_mov_b32 m0, s29
	v_lshl_add_u64 v[196:197], s[8:9], 0, v[0:1]
	ds_read_b128 v[166:169], v194 offset:32768
	ds_read_b128 v[170:173], v194 offset:33792
	ds_read_b128 v[174:177], v194 offset:34816
	ds_read_b128 v[178:181], v194 offset:35840
	ds_read_b128 v[182:185], v194 offset:36864
	ds_read_b128 v[186:189], v194 offset:37888
	ds_read_b128 v[200:203], v194 offset:38912
	ds_read_b128 v[204:207], v194 offset:39936
	global_load_lds_dwordx4 v[196:197], off
	v_lshl_add_u64 v[196:197], v[196:197], 0, s[70:71]
	s_mov_b32 m0, s92
	s_nop 0
	global_load_lds_dwordx4 v[196:197], off
	s_waitcnt vmcnt(8)
	s_waitcnt lgkmcnt(0)
	s_setprio 1
	s_barrier
	v_mfma_f32_16x16x32_bf16 v[126:129], v[130:133], v[166:169], v[126:129]
	v_mfma_f32_16x16x32_bf16 v[122:125], v[138:141], v[166:169], v[122:125]
	v_mfma_f32_16x16x32_bf16 v[118:121], v[130:133], v[174:177], v[118:121]
	v_mfma_f32_16x16x32_bf16 v[114:117], v[138:141], v[174:177], v[114:117]
	v_mfma_f32_16x16x32_bf16 v[110:113], v[130:133], v[182:185], v[110:113]
	v_mfma_f32_16x16x32_bf16 v[106:109], v[138:141], v[182:185], v[106:109]
	v_mfma_f32_16x16x32_bf16 v[102:105], v[130:133], v[200:203], v[102:105]
	v_mfma_f32_16x16x32_bf16 v[98:101], v[138:141], v[200:203], v[98:101]
	v_mfma_f32_16x16x32_bf16 v[126:129], v[134:137], v[170:173], v[126:129]
	v_mfma_f32_16x16x32_bf16 v[122:125], v[142:145], v[170:173], v[122:125]
	v_mfma_f32_16x16x32_bf16 v[118:121], v[134:137], v[178:181], v[118:121]
	v_mfma_f32_16x16x32_bf16 v[114:117], v[142:145], v[178:181], v[114:117]
	v_mfma_f32_16x16x32_bf16 v[110:113], v[134:137], v[186:189], v[110:113]
	v_mfma_f32_16x16x32_bf16 v[106:109], v[142:145], v[186:189], v[106:109]
	v_mfma_f32_16x16x32_bf16 v[102:105], v[134:137], v[204:207], v[102:105]
	v_mfma_f32_16x16x32_bf16 v[98:101], v[142:145], v[204:207], v[98:101]
	v_mfma_f32_16x16x32_bf16 v[62:65], v[146:149], v[166:169], v[62:65]
	v_mfma_f32_16x16x32_bf16 v[58:61], v[158:161], v[166:169], v[58:61]
	v_mfma_f32_16x16x32_bf16 v[54:57], v[146:149], v[174:177], v[54:57]
	v_mfma_f32_16x16x32_bf16 v[50:53], v[158:161], v[174:177], v[50:53]
	v_mfma_f32_16x16x32_bf16 v[46:49], v[146:149], v[182:185], v[46:49]
	v_mfma_f32_16x16x32_bf16 v[42:45], v[158:161], v[182:185], v[42:45]
	v_mfma_f32_16x16x32_bf16 v[38:41], v[146:149], v[200:203], v[38:41]
	v_mfma_f32_16x16x32_bf16 v[34:37], v[158:161], v[200:203], v[34:37]
	v_mfma_f32_16x16x32_bf16 v[62:65], v[150:153], v[170:173], v[62:65]
	v_mfma_f32_16x16x32_bf16 v[58:61], v[162:165], v[170:173], v[58:61]
	v_mfma_f32_16x16x32_bf16 v[54:57], v[150:153], v[178:181], v[54:57]
	v_mfma_f32_16x16x32_bf16 v[50:53], v[162:165], v[178:181], v[50:53]
	v_mfma_f32_16x16x32_bf16 v[46:49], v[150:153], v[186:189], v[46:49]
	v_mfma_f32_16x16x32_bf16 v[42:45], v[162:165], v[186:189], v[42:45]
	v_mfma_f32_16x16x32_bf16 v[38:41], v[150:153], v[204:207], v[38:41]
	v_mfma_f32_16x16x32_bf16 v[34:37], v[162:165], v[204:207], v[34:37]
	s_barrier
; #define PG8_STAGE(bufoff, gbase, unused) do { _Pragma("unroll") for (int _i = 0; _i < 2; ++_i) \
;         __builtin_amdgcn_global_load_lds((const unsigned*)((const char*)(gbase) + voff + _i * 8192), (LAS unsigned*)(lds + (bufoff) + ldsw + _i * 8192), 16, 0, 0); } while (0)
; #define PG8_LDA(dst, b, h) do { _Pragma("unroll") for (int m = 0; m < 4; ++m) _Pragma("unroll") for (int k = 0; k < 2; ++k) dst[m][k] = *(const LAS bf16x8*)(lds + PG8_SA(b, h) + aoff + m * 2048 + (FP8 ? k * 16 : k * 1024)); } while (0)
; #define PG8_WAIT_V(n) asm volatile("s_waitcnt vmcnt(" #n ")" ::: "memory")
; #define PG8_WAIT_L(n) asm volatile("s_waitcnt lgkmcnt(" #n ")" ::: "memory")
; #define PG8_BAR __builtin_amdgcn_s_barrier()
; #define PG8_SCHED __builtin_amdgcn_sched_barrier(0)
; template <class Epi, class Sched, bool ALIGN_EPI, bool SP2, int MODE  >
; __device__ __forceinline__ void gemm_phase(LAS unsigned char* lds, const Gemm g, const Sched S, const Epi E, unsigned long long& probe_acc, int epi_id, int wv) {
;     ...
;             PG8_WAIT_V(8); PG8_WAIT_L(0); PG8_BAR; PG8_MMA(0, 0, At, B0); PG8_MMA(0, 1, At, B1); PG8_BAR; PG8_SCHED;
;             PG8_LDA(At, 1, 1); PG8_STAGE(PG8_SB(1, 0), b3, voffB); PG8_STAGE(PG8_SB(1, 1), b3 + hB, voffB); PG8_STAGE(PG8_SA(1, 0), a3, voffA);
;             PG8_WAIT_V(8); PG8_WAIT_L(0); PG8_BAR; PG8_MMA(1, 0, At, B0); PG8_MMA(1, 1, At, B1); PG8_BAR; PG8_SCHED;
	s_setprio 0
	s_add_u32 s6, s6, 0x4000
	s_addc_u32 s7, s7, 0
	s_mov_b32 m0, s2
	v_lshl_add_u64 v[196:197], s[6:7], 0, v[0:1]
	s_add_u32 s6, s6, s13
	ds_read_b128 v[166:169], v194 offset:49152
	ds_read_b128 v[170:173], v194 offset:50176
	ds_read_b128 v[174:177], v194 offset:51200
	ds_read_b128 v[178:181], v194 offset:52224
	ds_read_b128 v[182:185], v194 offset:53248
	ds_read_b128 v[186:189], v194 offset:54272
	ds_read_b128 v[200:203], v194 offset:55296
	ds_read_b128 v[204:207], v194 offset:56320
	global_load_lds_dwordx4 v[196:197], off
	v_lshl_add_u64 v[196:197], v[196:197], 0, s[70:71]
	s_mov_b32 m0, s3
	s_addc_u32 s7, s7, 0
	global_load_lds_dwordx4 v[196:197], off
	v_lshl_add_u64 v[196:197], s[6:7], 0, v[0:1]
	s_mov_b32 m0, s12
	s_nop 0
	global_load_lds_dwordx4 v[196:197], off
	v_lshl_add_u64 v[196:197], v[196:197], 0, s[70:71]
	s_mov_b32 m0, s95
	s_nop 0
	global_load_lds_dwordx4 v[196:197], off
	v_lshl_add_u64 v[196:197], v[190:191], 0, s[76:77]
	s_mov_b32 m0, s50
	v_lshl_add_u64 v[190:191], v[190:191], 0, s[78:79]
	global_load_lds_dwordx4 v[196:197], off
	s_mov_b32 m0, s51
	s_nop 0
	global_load_lds_dwordx4 v[190:191], off
	s_waitcnt vmcnt(8)
	s_waitcnt lgkmcnt(0)
	s_setprio 1
	s_barrier
	v_mfma_f32_16x16x32_bf16 v[94:97], v[130:133], v[166:169], v[94:97]
	v_mfma_f32_16x16x32_bf16 v[90:93], v[138:141], v[166:169], v[90:93]
	v_mfma_f32_16x16x32_bf16 v[86:89], v[130:133], v[174:177], v[86:89]
	v_mfma_f32_16x16x32_bf16 v[82:85], v[138:141], v[174:177], v[82:85]
	v_mfma_f32_16x16x32_bf16 v[78:81], v[130:133], v[182:185], v[78:81]
	v_mfma_f32_16x16x32_bf16 v[74:77], v[138:141], v[182:185], v[74:77]
	v_mfma_f32_16x16x32_bf16 v[70:73], v[130:133], v[200:203], v[70:73]
	v_mfma_f32_16x16x32_bf16 v[66:69], v[138:141], v[200:203], v[66:69]
	v_mfma_f32_16x16x32_bf16 v[94:97], v[134:137], v[170:173], v[94:97]
	v_mfma_f32_16x16x32_bf16 v[90:93], v[142:145], v[170:173], v[90:93]
	v_mfma_f32_16x16x32_bf16 v[86:89], v[134:137], v[178:181], v[86:89]
	v_mfma_f32_16x16x32_bf16 v[82:85], v[142:145], v[178:181], v[82:85]
	v_mfma_f32_16x16x32_bf16 v[78:81], v[134:137], v[186:189], v[78:81]
	v_mfma_f32_16x16x32_bf16 v[74:77], v[142:145], v[186:189], v[74:77]
	v_mfma_f32_16x16x32_bf16 v[70:73], v[134:137], v[204:207], v[70:73]
	v_mfma_f32_16x16x32_bf16 v[66:69], v[142:145], v[204:207], v[66:69]
	v_mfma_f32_16x16x32_bf16 v[30:33], v[146:149], v[166:169], v[30:33]
	v_mfma_f32_16x16x32_bf16 v[26:29], v[158:161], v[166:169], v[26:29]
	v_mfma_f32_16x16x32_bf16 v[22:25], v[146:149], v[174:177], v[22:25]
	v_mfma_f32_16x16x32_bf16 v[18:21], v[158:161], v[174:177], v[18:21]
	v_mfma_f32_16x16x32_bf16 v[14:17], v[146:149], v[182:185], v[14:17]
	v_mfma_f32_16x16x32_bf16 v[10:13], v[158:161], v[182:185], v[10:13]
	v_mfma_f32_16x16x32_bf16 v[6:9], v[146:149], v[200:203], v[6:9]
	v_mfma_f32_16x16x32_bf16 v[2:5], v[158:161], v[200:203], v[2:5]
	v_mfma_f32_16x16x32_bf16 v[30:33], v[150:153], v[170:173], v[30:33]
	v_mfma_f32_16x16x32_bf16 v[26:29], v[162:165], v[170:173], v[26:29]
	v_mfma_f32_16x16x32_bf16 v[22:25], v[150:153], v[178:181], v[22:25]
	v_mfma_f32_16x16x32_bf16 v[18:21], v[162:165], v[178:181], v[18:21]
	v_mfma_f32_16x16x32_bf16 v[14:17], v[150:153], v[186:189], v[14:17]
	v_mfma_f32_16x16x32_bf16 v[10:13], v[162:165], v[186:189], v[10:13]
	v_mfma_f32_16x16x32_bf16 v[6:9], v[150:153], v[204:207], v[6:9]
	v_mfma_f32_16x16x32_bf16 v[2:5], v[162:165], v[204:207], v[2:5]
	s_barrier
	s_setprio 0
	s_add_u32 s10, s10, 0x8000
	s_addc_u32 s11, s11, 0
	s_add_u32 s4, s4, 0x8000
	s_addc_u32 s5, s5, 0
	s_cmp_ge_u32 s40, s58
	s_mov_b32 s6, s40
	.p2align 6

; template <class Epi, class Sched, bool ALIGN_EPI, bool SP2, int MODE  >
; __device__ __forceinline__ void gemm_phase(LAS unsigned char* lds, const Gemm g, const Sched S, const Epi E, unsigned long long& probe_acc, int epi_id, int wv) {
;     ...
;         for (int t = 0; t < nt; t += 2) {
;             const bool last = (t == nt - 2);
;             const char* a1 = cA + (size_t)(t + 1) * kstep;
;             const char* a2 = last ? nA : cA + (size_t)(t + 2) * kstep; const char* b2 = last ? nB : cB + (size_t)(t + 2) * kstep;
;             const char* a3 = a2 + kstep; const char* b3 = b2 + kstep;
;     ...
;         for (int a = 0; a < 2; ++a)
; #pragma unroll
;             for (int b = 0; b < 2; ++b)
; #pragma unroll
;                 for (int m = 0; m < 4; ++m)
; #pragma unroll
;                     for (int n = 0; n < 2; ++n) acc[a][b][m][n] = (f32x4){0.f, 0.f, 0.f, 0.f};
.LBB0_913:
	s_add_u32 s8, s4, s12
	s_addc_u32 s9, s5, 0
	s_add_u32 s34, s6, 0x8000
	v_mov_b32_e32 v2, 0
	s_waitcnt vmcnt(0)
	v_lshl_add_u64 v[130:131], s[8:9], 0, v[0:1]
	s_addc_u32 s35, s7, 0
	s_mov_b32 s46, -2
	s_mov_b64 s[6:7], 0
	s_waitcnt lgkmcnt(0)
	v_mov_b32_e32 v3, v2
	v_mov_b32_e32 v4, v2
	v_mov_b32_e32 v5, v2
	v_mov_b32_e32 v6, v2
	v_mov_b32_e32 v7, v2
	v_mov_b32_e32 v8, v2
	v_mov_b32_e32 v9, v2
	v_mov_b32_e32 v10, v2
	v_mov_b32_e32 v11, v2
	v_mov_b32_e32 v12, v2
	v_mov_b32_e32 v13, v2
	v_mov_b32_e32 v14, v2
	v_mov_b32_e32 v15, v2
	v_mov_b32_e32 v16, v2
	v_mov_b32_e32 v17, v2
	v_mov_b32_e32 v18, v2
	v_mov_b32_e32 v19, v2
	v_mov_b32_e32 v20, v2
	v_mov_b32_e32 v21, v2
	v_mov_b32_e32 v22, v2
	v_mov_b32_e32 v23, v2
	v_mov_b32_e32 v24, v2
	v_mov_b32_e32 v25, v2
	v_mov_b32_e32 v26, v2
	v_mov_b32_e32 v27, v2
	v_mov_b32_e32 v28, v2
	v_mov_b32_e32 v29, v2
	v_mov_b32_e32 v30, v2
	v_mov_b32_e32 v31, v2
	v_mov_b32_e32 v32, v2
	v_mov_b32_e32 v33, v2
	v_mov_b32_e32 v66, v2
	v_mov_b32_e32 v67, v2
	v_mov_b32_e32 v68, v2
	v_mov_b32_e32 v69, v2
	v_mov_b32_e32 v70, v2
	v_mov_b32_e32 v71, v2
	v_mov_b32_e32 v72, v2
	v_mov_b32_e32 v73, v2
	v_mov_b32_e32 v74, v2
	v_mov_b32_e32 v75, v2
	v_mov_b32_e32 v76, v2
	v_mov_b32_e32 v77, v2
	v_mov_b32_e32 v78, v2
	v_mov_b32_e32 v79, v2
	v_mov_b32_e32 v80, v2
	v_mov_b32_e32 v81, v2
	v_mov_b32_e32 v82, v2
	v_mov_b32_e32 v83, v2
	v_mov_b32_e32 v84, v2
	v_mov_b32_e32 v85, v2
	v_mov_b32_e32 v86, v2
	v_mov_b32_e32 v87, v2
	v_mov_b32_e32 v88, v2
	v_mov_b32_e32 v89, v2
	v_mov_b32_e32 v90, v2
	v_mov_b32_e32 v91, v2
	v_mov_b32_e32 v92, v2
	v_mov_b32_e32 v93, v2
	v_mov_b32_e32 v94, v2
	v_mov_b32_e32 v95, v2
	v_mov_b32_e32 v96, v2
	v_mov_b32_e32 v97, v2
	v_mov_b32_e32 v34, v2
	v_mov_b32_e32 v35, v2
	v_mov_b32_e32 v36, v2
	v_mov_b32_e32 v37, v2
	v_mov_b32_e32 v38, v2
	v_mov_b32_e32 v39, v2
	v_mov_b32_e32 v40, v2
	v_mov_b32_e32 v41, v2
	v_mov_b32_e32 v42, v2
	v_mov_b32_e32 v43, v2
	v_mov_b32_e32 v44, v2
	v_mov_b32_e32 v45, v2
	v_mov_b32_e32 v46, v2
	v_mov_b32_e32 v47, v2
	v_mov_b32_e32 v48, v2
	v_mov_b32_e32 v49, v2
	v_mov_b32_e32 v50, v2
	v_mov_b32_e32 v51, v2
	v_mov_b32_e32 v52, v2
	v_mov_b32_e32 v53, v2
	v_mov_b32_e32 v54, v2
	v_mov_b32_e32 v55, v2
	v_mov_b32_e32 v56, v2
	v_mov_b32_e32 v57, v2
	v_mov_b32_e32 v58, v2
	v_mov_b32_e32 v59, v2
	v_mov_b32_e32 v60, v2
	v_mov_b32_e32 v61, v2
	v_mov_b32_e32 v62, v2
	v_mov_b32_e32 v63, v2
	v_mov_b32_e32 v64, v2
	v_mov_b32_e32 v65, v2
	v_mov_b32_e32 v98, v2
	v_mov_b32_e32 v99, v2
	v_mov_b32_e32 v100, v2
	v_mov_b32_e32 v101, v2
	v_mov_b32_e32 v102, v2
	v_mov_b32_e32 v103, v2
	v_mov_b32_e32 v104, v2
	v_mov_b32_e32 v105, v2
	v_mov_b32_e32 v106, v2
	v_mov_b32_e32 v107, v2
	v_mov_b32_e32 v108, v2
	v_mov_b32_e32 v109, v2
	v_mov_b32_e32 v110, v2
	v_mov_b32_e32 v111, v2
	v_mov_b32_e32 v112, v2
	v_mov_b32_e32 v113, v2
	v_mov_b32_e32 v114, v2
	v_mov_b32_e32 v115, v2
	v_mov_b32_e32 v116, v2
	v_mov_b32_e32 v117, v2
	v_mov_b32_e32 v118, v2
	v_mov_b32_e32 v119, v2
	v_mov_b32_e32 v120, v2
	v_mov_b32_e32 v121, v2
	v_mov_b32_e32 v122, v2
	v_mov_b32_e32 v123, v2
	v_mov_b32_e32 v124, v2
	v_mov_b32_e32 v125, v2
	v_mov_b32_e32 v126, v2
	v_mov_b32_e32 v127, v2
	v_mov_b32_e32 v128, v2
	v_mov_b32_e32 v129, v2
	s_mov_b64 s[42:43], 0xb0000
	v_xor_b32_e32 v193, 16, v192
	.p2align 6

; #define PG8_STAGE(bufoff, gbase, unused) do { _Pragma("unroll") for (int _i = 0; _i < 2; ++_i) \
;         __builtin_amdgcn_global_load_lds((const unsigned*)((const char*)(gbase) + voff + _i * 8192), (LAS unsigned*)(lds + (bufoff) + ldsw + _i * 8192), 16, 0, 0); } while (0)
; #define PG8_LDA(dst, b, h) do { _Pragma("unroll") for (int m = 0; m < 4; ++m) _Pragma("unroll") for (int k = 0; k < 2; ++k) dst[m][k] = *(const LAS bf16x8*)(lds + PG8_SA(b, h) + aoff + m * 2048 + (FP8 ? k * 16 : k * 1024)); } while (0)
; #define PG8_LDB(dst, b, h) do { _Pragma("unroll") for (int n = 0; n < 2; ++n) _Pragma("unroll") for (int k = 0; k < 2; ++k) dst[n][k] = *(const LAS bf16x8*)(lds + PG8_SB(b, h) + boff + n * 2048 + (FP8 ? k * 16 : k * 1024)); } while (0)
; #define PG8_WAIT_V(n) asm volatile("s_waitcnt vmcnt(" #n ")" ::: "memory")
; #define PG8_WAIT_L(n) asm volatile("s_waitcnt lgkmcnt(" #n ")" ::: "memory")
; #define PG8_BAR __builtin_amdgcn_s_barrier()
; #define PG8_SCHED __builtin_amdgcn_sched_barrier(0)
; template <class Epi, class Sched, bool ALIGN_EPI, bool SP2, int MODE  >
; __device__ __forceinline__ void gemm_phase(LAS unsigned char* lds, const Gemm g, const Sched S, const Epi E, unsigned long long& probe_acc, int epi_id, int wv) {
;     ...
;         const char* nA = has_next ? (const char*)g.A + (size_t)nxt.pm * tA + (g.gt ? (size_t)(nxt.pn / g.gt) * gK2 : 0) : cA; const char* nB = has_next ? (const char*)g.Bt + (size_t)nxt.pn * tB : cB;
;         for (int t = 0; t < nt; t += 2) {
;             const bool last = (t == nt - 2);
;             const char* a1 = cA + (size_t)(t + 1) * kstep;
;             const char* a2 = last ? nA : cA + (size_t)(t + 2) * kstep; const char* b2 = last ? nB : cB + (size_t)(t + 2) * kstep;
;             const char* a3 = a2 + kstep; const char* b3 = b2 + kstep;
;             if constexpr (SP2) {
;             PG8_LDB(B0, 0, 0); PG8_LDB(B1, 0, 1); PG8_SCHED; PG8_LDA(At, 0, 0); PG8_STAGE(PG8_SA(1, 1), a1 + hA, voffA);
;             PG8_WAIT_V(8); PG8_WAIT_L(0); PG8_BAR; PG8_MMA(0, 0, At, B0); PG8_MMA(0, 1, At, B1); PG8_BAR; PG8_SCHED;
;             PG8_LDA(At, 0, 1); PG8_STAGE(PG8_SB(0, 0), b2, voffB); PG8_STAGE(PG8_SB(0, 1), b2 + hB, voffB); PG8_STAGE(PG8_SA(0, 0), a2, voffA);
;             PG8_WAIT_V(8); PG8_WAIT_L(0); PG8_BAR; PG8_MMA(1, 0, At, B0); PG8_MMA(1, 1, At, B1); PG8_BAR; PG8_SCHED;
.LBB0_1153:
	s_add_u32 s8, s4, s40
	s_addc_u32 s9, s5, 0
	s_add_u32 s10, s6, 0x8000
	s_waitcnt vmcnt(0)
	v_lshl_add_u64 v[130:131], s[8:9], 0, v[0:1]
	s_addc_u32 s11, s7, 0
	s_mov_b32 s34, -2
	s_mov_b64 s[6:7], 0
	s_waitcnt lgkmcnt(0)
	s_mov_b64 s[42:43], 0xb0000
	v_add_u32_e32 v144, s90, v200
	v_add_u32_e32 v160, s15, v200
	s_add_u32 s8, s4, s6
	ds_read_b128 v[132:135], v144
	ds_read_b128 v[136:139], v144 offset:1024
	ds_read_b128 v[140:143], v144 offset:2048
	ds_read_b128 v[144:147], v144 offset:3072
	ds_read_b128 v[148:151], v160
	ds_read_b128 v[152:155], v160 offset:1024
	ds_read_b128 v[156:159], v160 offset:2048
	ds_read_b128 v[164:167], v160 offset:3072
	s_addc_u32 s9, s5, s7
	s_add_u32 s8, s8, 0x8000
	s_addc_u32 s9, s9, 0
	s_add_u32 s28, s10, s6
	s_addc_u32 s29, s11, s7
	s_cmp_eq_u32 s6, 0xa8000
	s_cselect_b32 s9, s67, s9
	s_cselect_b32 s8, s66, s8
	s_cselect_b32 vcc_hi, s87, s29
	s_cselect_b32 vcc_lo, s86, s28
	v_lshl_add_u64 v[160:161], v[130:131], 0, s[6:7]
	v_lshl_add_u64 v[196:197], v[160:161], 0, s[76:77]
	s_add_i32 m0, s0, 0xc000
	ds_read_b128 v[168:171], v201
	ds_read_b128 v[172:175], v201 offset:1024
	ds_read_b128 v[176:179], v201 offset:2048
	ds_read_b128 v[180:183], v201 offset:3072
	ds_read_b128 v[184:187], v201 offset:4096
	ds_read_b128 v[188:191], v201 offset:5120
	ds_read_b128 v[192:195], v201 offset:6144
	ds_read_b128 v[212:215], v201 offset:7168
	global_load_lds_dwordx4 v[196:197], off
	v_lshl_add_u64 v[160:161], v[160:161], 0, s[78:79]
	s_add_i32 m0, s0, 0xe000
	s_nop 0
	global_load_lds_dwordx4 v[160:161], off
	s_waitcnt vmcnt(8)
	s_waitcnt lgkmcnt(0)
	s_setprio 1
	s_barrier
	v_mfma_i32_16x16x64_i8 v[122:125], v[132:135], v[168:171], 0
	v_mfma_i32_16x16x64_i8 v[126:129], v[140:143], v[168:171], 0
	v_mfma_i32_16x16x64_i8 v[114:117], v[132:135], v[176:179], 0
	v_mfma_i32_16x16x64_i8 v[118:121], v[140:143], v[176:179], 0
	v_mfma_i32_16x16x64_i8 v[106:109], v[132:135], v[184:187], 0
	v_mfma_i32_16x16x64_i8 v[110:113], v[140:143], v[184:187], 0
	v_mfma_i32_16x16x64_i8 v[98:101], v[132:135], v[192:195], 0
	v_mfma_i32_16x16x64_i8 v[102:105], v[140:143], v[192:195], 0
	v_mfma_i32_16x16x64_i8 v[122:125], v[136:139], v[172:175], v[122:125]
	v_mfma_i32_16x16x64_i8 v[126:129], v[144:147], v[172:175], v[126:129]
	v_mfma_i32_16x16x64_i8 v[114:117], v[136:139], v[180:183], v[114:117]
	v_mfma_i32_16x16x64_i8 v[118:121], v[144:147], v[180:183], v[118:121]
	v_mfma_i32_16x16x64_i8 v[106:109], v[136:139], v[188:191], v[106:109]
	v_mfma_i32_16x16x64_i8 v[110:113], v[144:147], v[188:191], v[110:113]
	v_mfma_i32_16x16x64_i8 v[98:101], v[136:139], v[212:215], v[98:101]
	v_mfma_i32_16x16x64_i8 v[102:105], v[144:147], v[212:215], v[102:105]
	v_mfma_i32_16x16x64_i8 v[58:61], v[148:151], v[168:171], 0
	v_mfma_i32_16x16x64_i8 v[62:65], v[156:159], v[168:171], 0
	v_mfma_i32_16x16x64_i8 v[50:53], v[148:151], v[176:179], 0
	v_mfma_i32_16x16x64_i8 v[54:57], v[156:159], v[176:179], 0
	v_mfma_i32_16x16x64_i8 v[42:45], v[148:151], v[184:187], 0
	v_mfma_i32_16x16x64_i8 v[46:49], v[156:159], v[184:187], 0
	v_mfma_i32_16x16x64_i8 v[34:37], v[148:151], v[192:195], 0
	v_mfma_i32_16x16x64_i8 v[38:41], v[156:159], v[192:195], 0
	v_mfma_i32_16x16x64_i8 v[58:61], v[152:155], v[172:175], v[58:61]
	v_mfma_i32_16x16x64_i8 v[62:65], v[164:167], v[172:175], v[62:65]
	v_mfma_i32_16x16x64_i8 v[50:53], v[152:155], v[180:183], v[50:53]
	v_mfma_i32_16x16x64_i8 v[54:57], v[164:167], v[180:183], v[54:57]
	v_mfma_i32_16x16x64_i8 v[42:45], v[152:155], v[188:191], v[42:45]
	v_mfma_i32_16x16x64_i8 v[46:49], v[164:167], v[188:191], v[46:49]
	v_mfma_i32_16x16x64_i8 v[34:37], v[152:155], v[212:215], v[34:37]
	v_mfma_i32_16x16x64_i8 v[38:41], v[164:167], v[212:215], v[38:41]
	s_barrier
	s_setprio 0
	s_mov_b32 m0, s91
	v_lshl_add_u64 v[160:161], vcc, 0, v[0:1]
	ds_read_b128 v[168:171], v201 offset:16384
	ds_read_b128 v[172:175], v201 offset:17408
	ds_read_b128 v[176:179], v201 offset:18432
	ds_read_b128 v[180:183], v201 offset:19456
	ds_read_b128 v[184:187], v201 offset:20480
	ds_read_b128 v[188:191], v201 offset:21504
	ds_read_b128 v[192:195], v201 offset:22528
	ds_read_b128 v[212:215], v201 offset:23552
	global_load_lds_dwordx4 v[160:161], off
	v_lshl_add_u64 v[196:197], v[160:161], 0, s[70:71]
	s_mov_b32 m0, s14
	s_nop 0
	global_load_lds_dwordx4 v[196:197], off
	v_lshl_add_u64 v[196:197], v[160:161], 0, s[42:43]
	s_mov_b32 m0, s26
	s_nop 0
	global_load_lds_dwordx4 v[196:197], off
	v_lshl_add_u64 v[196:197], v[160:161], 0, s[48:49]
	s_mov_b32 m0, s27
	s_nop 0
	global_load_lds_dwordx4 v[196:197], off
	v_lshl_add_u64 v[196:197], s[8:9], 0, v[0:1]
	s_mov_b32 m0, s0
	v_lshl_add_u64 v[202:203], v[196:197], 0, s[70:71]
	global_load_lds_dwordx4 v[196:197], off
	s_mov_b32 m0, s1
	s_nop 0
	global_load_lds_dwordx4 v[202:203], off
	s_waitcnt vmcnt(8)
	s_waitcnt lgkmcnt(0)
	s_setprio 1
	s_barrier
; #define PG8_STAGE(bufoff, gbase, unused) do { _Pragma("unroll") for (int _i = 0; _i < 2; ++_i) \
;         __builtin_amdgcn_global_load_lds((const unsigned*)((const char*)(gbase) + voff + _i * 8192), (LAS unsigned*)(lds + (bufoff) + ldsw + _i * 8192), 16, 0, 0); } while (0)
; #define PG8_LDA(dst, b, h) do { _Pragma("unroll") for (int m = 0; m < 4; ++m) _Pragma("unroll") for (int k = 0; k < 2; ++k) dst[m][k] = *(const LAS bf16x8*)(lds + PG8_SA(b, h) + aoff + m * 2048 + (FP8 ? k * 16 : k * 1024)); } while (0)
; #define PG8_LDB(dst, b, h) do { _Pragma("unroll") for (int n = 0; n < 2; ++n) _Pragma("unroll") for (int k = 0; k < 2; ++k) dst[n][k] = *(const LAS bf16x8*)(lds + PG8_SB(b, h) + boff + n * 2048 + (FP8 ? k * 16 : k * 1024)); } while (0)
; #define PG8_WAIT_V(n) asm volatile("s_waitcnt vmcnt(" #n ")" ::: "memory")
; #define PG8_WAIT_L(n) asm volatile("s_waitcnt lgkmcnt(" #n ")" ::: "memory")
; #define PG8_BAR __builtin_amdgcn_s_barrier()
; #define PG8_SCHED __builtin_amdgcn_sched_barrier(0)
; template <class Epi, class Sched, bool ALIGN_EPI, bool SP2, int MODE  >
; __device__ __forceinline__ void gemm_phase(LAS unsigned char* lds, const Gemm g, const Sched S, const Epi E, unsigned long long& probe_acc, int epi_id, int wv) {
;     ...
;             PG8_WAIT_V(8); PG8_WAIT_L(0); PG8_BAR; PG8_MMA(1, 0, At, B0); PG8_MMA(1, 1, At, B1); PG8_BAR; PG8_SCHED;
;             PG8_LDB(B0, 1, 0); PG8_LDB(B1, 1, 1); PG8_SCHED; PG8_LDA(At, 1, 0); PG8_STAGE(PG8_SA(0, 1), a2 + hA, voffA);
;             PG8_WAIT_V(8); PG8_WAIT_L(0); PG8_BAR; PG8_MMA(0, 0, At, B0); PG8_MMA(0, 1, At, B1); PG8_BAR; PG8_SCHED;
	v_mfma_i32_16x16x64_i8 v[90:93], v[132:135], v[168:171], 0
	v_mfma_i32_16x16x64_i8 v[94:97], v[140:143], v[168:171], 0
	v_mfma_i32_16x16x64_i8 v[82:85], v[132:135], v[176:179], 0
	v_mfma_i32_16x16x64_i8 v[86:89], v[140:143], v[176:179], 0
	v_mfma_i32_16x16x64_i8 v[74:77], v[132:135], v[184:187], 0
	v_mfma_i32_16x16x64_i8 v[78:81], v[140:143], v[184:187], 0
	v_mfma_i32_16x16x64_i8 v[66:69], v[132:135], v[192:195], 0
	v_mfma_i32_16x16x64_i8 v[70:73], v[140:143], v[192:195], 0
	v_mfma_i32_16x16x64_i8 v[90:93], v[136:139], v[172:175], v[90:93]
	v_mfma_i32_16x16x64_i8 v[94:97], v[144:147], v[172:175], v[94:97]
	v_mfma_i32_16x16x64_i8 v[82:85], v[136:139], v[180:183], v[82:85]
	v_mfma_i32_16x16x64_i8 v[86:89], v[144:147], v[180:183], v[86:89]
	v_mfma_i32_16x16x64_i8 v[74:77], v[136:139], v[188:191], v[74:77]
	v_mfma_i32_16x16x64_i8 v[78:81], v[144:147], v[188:191], v[78:81]
	v_mfma_i32_16x16x64_i8 v[66:69], v[136:139], v[212:215], v[66:69]
	v_mfma_i32_16x16x64_i8 v[70:73], v[144:147], v[212:215], v[70:73]
	v_mfma_i32_16x16x64_i8 v[26:29], v[148:151], v[168:171], 0
	v_mfma_i32_16x16x64_i8 v[30:33], v[156:159], v[168:171], 0
	v_mfma_i32_16x16x64_i8 v[18:21], v[148:151], v[176:179], 0
	v_mfma_i32_16x16x64_i8 v[22:25], v[156:159], v[176:179], 0
	v_mfma_i32_16x16x64_i8 v[10:13], v[148:151], v[184:187], 0
	v_mfma_i32_16x16x64_i8 v[14:17], v[156:159], v[184:187], 0
	v_mfma_i32_16x16x64_i8 v[2:5], v[148:151], v[192:195], 0
	v_mfma_i32_16x16x64_i8 v[6:9], v[156:159], v[192:195], 0
	v_mfma_i32_16x16x64_i8 v[26:29], v[152:155], v[172:175], v[26:29]
	v_mfma_i32_16x16x64_i8 v[30:33], v[164:167], v[172:175], v[30:33]
	v_mfma_i32_16x16x64_i8 v[18:21], v[152:155], v[180:183], v[18:21]
	v_mfma_i32_16x16x64_i8 v[22:25], v[164:167], v[180:183], v[22:25]
	v_mfma_i32_16x16x64_i8 v[10:13], v[152:155], v[188:191], v[10:13]
	v_mfma_i32_16x16x64_i8 v[14:17], v[164:167], v[188:191], v[14:17]
	v_mfma_i32_16x16x64_i8 v[2:5], v[152:155], v[212:215], v[2:5]
	v_mfma_i32_16x16x64_i8 v[6:9], v[164:167], v[212:215], v[6:9]
	s_barrier
	s_setprio 0
	v_add_u32_e32 v144, s88, v200
	v_add_u32_e32 v162, s95, v200
	ds_read_b128 v[132:135], v144
	ds_read_b128 v[136:139], v144 offset:1024
	ds_read_b128 v[140:143], v144 offset:2048
	ds_read_b128 v[144:147], v144 offset:3072
	ds_read_b128 v[148:151], v162
	ds_read_b128 v[152:155], v162 offset:1024
	ds_read_b128 v[156:159], v162 offset:2048
	ds_read_b128 v[164:167], v162 offset:3072
	s_add_u32 s8, s8, s40
	s_addc_u32 s9, s9, 0
	s_mov_b32 m0, s36
	v_lshl_add_u64 v[202:203], s[8:9], 0, v[0:1]
	ds_read_b128 v[168:171], v201 offset:32768
	ds_read_b128 v[172:175], v201 offset:33792
	ds_read_b128 v[176:179], v201 offset:34816
	ds_read_b128 v[180:183], v201 offset:35840
	ds_read_b128 v[184:187], v201 offset:36864
	ds_read_b128 v[188:191], v201 offset:37888
	ds_read_b128 v[192:195], v201 offset:38912
	ds_read_b128 v[212:215], v201 offset:39936
	global_load_lds_dwordx4 v[202:203], off
	v_lshl_add_u64 v[202:203], v[202:203], 0, s[70:71]
	s_mov_b32 m0, s37
	s_nop 0
	global_load_lds_dwordx4 v[202:203], off
	s_waitcnt vmcnt(8)
	s_waitcnt lgkmcnt(0)
	s_setprio 1
	s_barrier
	v_mfma_i32_16x16x64_i8 v[122:125], v[132:135], v[168:171], v[122:125]
	v_mfma_i32_16x16x64_i8 v[126:129], v[140:143], v[168:171], v[126:129]
	v_mfma_i32_16x16x64_i8 v[114:117], v[132:135], v[176:179], v[114:117]
	v_mfma_i32_16x16x64_i8 v[118:121], v[140:143], v[176:179], v[118:121]
	v_mfma_i32_16x16x64_i8 v[106:109], v[132:135], v[184:187], v[106:109]
	v_mfma_i32_16x16x64_i8 v[110:113], v[140:143], v[184:187], v[110:113]
	v_mfma_i32_16x16x64_i8 v[98:101], v[132:135], v[192:195], v[98:101]
	v_mfma_i32_16x16x64_i8 v[102:105], v[140:143], v[192:195], v[102:105]
	v_mfma_i32_16x16x64_i8 v[122:125], v[136:139], v[172:175], v[122:125]
	v_mfma_i32_16x16x64_i8 v[126:129], v[144:147], v[172:175], v[126:129]
	v_mfma_i32_16x16x64_i8 v[114:117], v[136:139], v[180:183], v[114:117]
	v_mfma_i32_16x16x64_i8 v[118:121], v[144:147], v[180:183], v[118:121]
	v_mfma_i32_16x16x64_i8 v[106:109], v[136:139], v[188:191], v[106:109]
	v_mfma_i32_16x16x64_i8 v[110:113], v[144:147], v[188:191], v[110:113]
	v_mfma_i32_16x16x64_i8 v[98:101], v[136:139], v[212:215], v[98:101]
	v_mfma_i32_16x16x64_i8 v[102:105], v[144:147], v[212:215], v[102:105]
	v_mfma_i32_16x16x64_i8 v[58:61], v[148:151], v[168:171], v[58:61]
	v_mfma_i32_16x16x64_i8 v[62:65], v[156:159], v[168:171], v[62:65]
	v_mfma_i32_16x16x64_i8 v[50:53], v[148:151], v[176:179], v[50:53]
	v_mfma_i32_16x16x64_i8 v[54:57], v[156:159], v[176:179], v[54:57]
	v_mfma_i32_16x16x64_i8 v[42:45], v[148:151], v[184:187], v[42:45]
	v_mfma_i32_16x16x64_i8 v[46:49], v[156:159], v[184:187], v[46:49]
	v_mfma_i32_16x16x64_i8 v[34:37], v[148:151], v[192:195], v[34:37]
	v_mfma_i32_16x16x64_i8 v[38:41], v[156:159], v[192:195], v[38:41]
	v_mfma_i32_16x16x64_i8 v[58:61], v[152:155], v[172:175], v[58:61]
	v_mfma_i32_16x16x64_i8 v[62:65], v[164:167], v[172:175], v[62:65]
	v_mfma_i32_16x16x64_i8 v[50:53], v[152:155], v[180:183], v[50:53]
	v_mfma_i32_16x16x64_i8 v[54:57], v[164:167], v[180:183], v[54:57]
	v_mfma_i32_16x16x64_i8 v[42:45], v[152:155], v[188:191], v[42:45]
	v_mfma_i32_16x16x64_i8 v[46:49], v[164:167], v[188:191], v[46:49]
	v_mfma_i32_16x16x64_i8 v[34:37], v[152:155], v[212:215], v[34:37]
	v_mfma_i32_16x16x64_i8 v[38:41], v[164:167], v[212:215], v[38:41]
	s_barrier
; #define PG8_STAGE(bufoff, gbase, unused) do { _Pragma("unroll") for (int _i = 0; _i < 2; ++_i) \
;         __builtin_amdgcn_global_load_lds((const unsigned*)((const char*)(gbase) + voff + _i * 8192), (LAS unsigned*)(lds + (bufoff) + ldsw + _i * 8192), 16, 0, 0); } while (0)
; #define PG8_LDA(dst, b, h) do { _Pragma("unroll") for (int m = 0; m < 4; ++m) _Pragma("unroll") for (int k = 0; k < 2; ++k) dst[m][k] = *(const LAS bf16x8*)(lds + PG8_SA(b, h) + aoff + m * 2048 + (FP8 ? k * 16 : k * 1024)); } while (0)
; #define PG8_WAIT_V(n) asm volatile("s_waitcnt vmcnt(" #n ")" ::: "memory")
; #define PG8_WAIT_L(n) asm volatile("s_waitcnt lgkmcnt(" #n ")" ::: "memory")
; #define PG8_BAR __builtin_amdgcn_s_barrier()
; #define PG8_SCHED __builtin_amdgcn_sched_barrier(0)
; template <class Epi, class Sched, bool ALIGN_EPI, bool SP2, int MODE  >
; __device__ __forceinline__ void gemm_phase(LAS unsigned char* lds, const Gemm g, const Sched S, const Epi E, unsigned long long& probe_acc, int epi_id, int wv) {
;     ...
;             PG8_WAIT_V(8); PG8_WAIT_L(0); PG8_BAR; PG8_MMA(0, 0, At, B0); PG8_MMA(0, 1, At, B1); PG8_BAR; PG8_SCHED;
;             PG8_LDA(At, 1, 1); PG8_STAGE(PG8_SB(1, 0), b3, voffB); PG8_STAGE(PG8_SB(1, 1), b3 + hB, voffB); PG8_STAGE(PG8_SA(1, 0), a3, voffA);
;             PG8_WAIT_V(8); PG8_WAIT_L(0); PG8_BAR; PG8_MMA(1, 0, At, B0); PG8_MMA(1, 1, At, B1); PG8_BAR; PG8_SCHED;
	s_setprio 0
	s_mov_b32 m0, s89
	v_lshl_add_u64 v[202:203], v[160:161], 0, s[76:77]
	ds_read_b128 v[168:171], v201 offset:49152
	ds_read_b128 v[172:175], v201 offset:50176
	ds_read_b128 v[176:179], v201 offset:51200
	ds_read_b128 v[180:183], v201 offset:52224
	ds_read_b128 v[184:187], v201 offset:53248
	ds_read_b128 v[188:191], v201 offset:54272
	ds_read_b128 v[192:195], v201 offset:55296
	ds_read_b128 v[212:215], v201 offset:56320
	global_load_lds_dwordx4 v[202:203], off
	v_lshl_add_u64 v[202:203], v[160:161], 0, s[78:79]
	s_mov_b32 m0, s92
	s_nop 0
	global_load_lds_dwordx4 v[202:203], off
	v_lshl_add_u64 v[202:203], v[160:161], 0, s[44:45]
	s_mov_b32 m0, s84
	v_lshl_add_u64 v[160:161], v[160:161], 0, s[56:57]
	global_load_lds_dwordx4 v[202:203], off
	s_mov_b32 m0, s12
	s_nop 0
	global_load_lds_dwordx4 v[160:161], off
	v_lshl_add_u64 v[160:161], v[196:197], 0, s[76:77]
	s_mov_b32 m0, s93
	s_nop 0
	global_load_lds_dwordx4 v[160:161], off
	v_lshl_add_u64 v[160:161], v[196:197], 0, s[78:79]
	s_mov_b32 m0, s94
	s_nop 0
	global_load_lds_dwordx4 v[160:161], off
	s_waitcnt vmcnt(8)
	s_waitcnt lgkmcnt(0)
	s_setprio 1
	s_barrier
	v_mfma_i32_16x16x64_i8 v[90:93], v[132:135], v[168:171], v[90:93]
	v_mfma_i32_16x16x64_i8 v[94:97], v[140:143], v[168:171], v[94:97]
	v_mfma_i32_16x16x64_i8 v[82:85], v[132:135], v[176:179], v[82:85]
	v_mfma_i32_16x16x64_i8 v[86:89], v[140:143], v[176:179], v[86:89]
	v_mfma_i32_16x16x64_i8 v[74:77], v[132:135], v[184:187], v[74:77]
	v_mfma_i32_16x16x64_i8 v[78:81], v[140:143], v[184:187], v[78:81]
	v_mfma_i32_16x16x64_i8 v[66:69], v[132:135], v[192:195], v[66:69]
	v_mfma_i32_16x16x64_i8 v[70:73], v[140:143], v[192:195], v[70:73]
	v_mfma_i32_16x16x64_i8 v[90:93], v[136:139], v[172:175], v[90:93]
	v_mfma_i32_16x16x64_i8 v[94:97], v[144:147], v[172:175], v[94:97]
	v_mfma_i32_16x16x64_i8 v[82:85], v[136:139], v[180:183], v[82:85]
	v_mfma_i32_16x16x64_i8 v[86:89], v[144:147], v[180:183], v[86:89]
	v_mfma_i32_16x16x64_i8 v[74:77], v[136:139], v[188:191], v[74:77]
	v_mfma_i32_16x16x64_i8 v[78:81], v[144:147], v[188:191], v[78:81]
	v_mfma_i32_16x16x64_i8 v[66:69], v[136:139], v[212:215], v[66:69]
	v_mfma_i32_16x16x64_i8 v[70:73], v[144:147], v[212:215], v[70:73]
	v_mfma_i32_16x16x64_i8 v[26:29], v[148:151], v[168:171], v[26:29]
	v_mfma_i32_16x16x64_i8 v[30:33], v[156:159], v[168:171], v[30:33]
	v_mfma_i32_16x16x64_i8 v[18:21], v[148:151], v[176:179], v[18:21]
	v_mfma_i32_16x16x64_i8 v[22:25], v[156:159], v[176:179], v[22:25]
	v_mfma_i32_16x16x64_i8 v[10:13], v[148:151], v[184:187], v[10:13]
	v_mfma_i32_16x16x64_i8 v[14:17], v[156:159], v[184:187], v[14:17]
	v_mfma_i32_16x16x64_i8 v[2:5], v[148:151], v[192:195], v[2:5]
	v_mfma_i32_16x16x64_i8 v[6:9], v[156:159], v[192:195], v[6:9]
	v_mfma_i32_16x16x64_i8 v[26:29], v[152:155], v[172:175], v[26:29]
	v_mfma_i32_16x16x64_i8 v[30:33], v[164:167], v[172:175], v[30:33]
	v_mfma_i32_16x16x64_i8 v[18:21], v[152:155], v[180:183], v[18:21]
	v_mfma_i32_16x16x64_i8 v[22:25], v[164:167], v[180:183], v[22:25]
	v_mfma_i32_16x16x64_i8 v[10:13], v[152:155], v[188:191], v[10:13]
	v_mfma_i32_16x16x64_i8 v[14:17], v[164:167], v[188:191], v[14:17]
	v_mfma_i32_16x16x64_i8 v[2:5], v[152:155], v[212:215], v[2:5]
	v_mfma_i32_16x16x64_i8 v[6:9], v[164:167], v[212:215], v[6:9]
	s_barrier
	s_setprio 0
	s_add_i32 s34, s34, 2
	s_add_u32 s6, s6, 0x8000
	s_addc_u32 s7, s7, 0
	s_cmp_gt_u32 s34, 41
	.p2align 6
